# residual epilogues: row-sum atomics of the first seven row groups deferred and issued together after the last row group (no atomic round trip in front of each row group's loads)
# speedup vs baseline: 1.0099x; 1.0010x over previous
;     __device__ __forceinline__ void operator()(const pg8::f32x4 (&acc)[2][2][4][2], const pg8::Unit& u, int wr, int wc, int fr, int fq) const {
;         const bool isctx = u.pm >= 256;
;         const int prow0 = (isctx ? (u.pm - 256) : u.pm) * 256;
;         const float* xin = isctx ? xin_ctx : xin_lat; float* xout = isctx ? xout_ctx : xout_lat;
;         const int brow = isctx ? 16 : (u.pm >> 4);
;         const float* gp = modg + (size_t)brow * 6144;
;         const int col0 = u.pn * 256 + wc * 32 + 8 * fq;
;         f32x4 gv[2][2], gm[2][2];
; #pragma unroll
;         for (int bj = 0; bj < 2; ++bj)
; #pragma unroll
;             for (int n = 0; n < 2; ++n) {
;                 gv[bj][n] = *(const f32x4*)(gp + col0 + bj * 128 + 4 * n);
;                 if (has_next) { const f32x4 g_ = *(const f32x4*)(gain_n + col0 + bj * 128 + 4 * n), s_ = *(const f32x4*)(modn + (size_t)brow * 6144 + col0 + bj * 128 + 4 * n); gm[bj][n] = g_ * (1.0f + s_); }
;                 else gm[bj][n] = (f32x4){0.f, 0.f, 0.f, 0.f};
;             }
; #pragma unroll
;         for (int it = 0; it < 8; ++it) {
;             const int ai = it >> 2, m = it & 3;
;             const int rl = ai * 128 + wr * 64 + m * 16 + fr;
;             const size_t off = (size_t)(prow0 + rl) * DM + col0;
;             f32x4 cur[2][2];
; #pragma unroll
;             for (int bj = 0; bj < 2; ++bj) { cur[bj][0] = *(const f32x4*)(xin + off + bj * 128); cur[bj][1] = *(const f32x4*)(xin + off + bj * 128 + 4); }
;             float ss = 0.f;
; #pragma unroll
;             for (int bj = 0; bj < 2; ++bj) {
;                 f32x4 dl0 = gv[bj][0] * acc[ai][bj][m][0], dl1 = gv[bj][1] * acc[ai][bj][m][1];
;                 bf16* dp = d1 + (size_t)(u.pm * 256 + rl) * DM + col0 + bj * 128;
;                 if (dmode == 2) {
;                     const u32x4 dw = *(const u32x4*)dp;
;                     dl0 += (f32x4){bflo(dw[0]), bfhi(dw[0]), bflo(dw[1]), bfhi(dw[1])}; dl1 += (f32x4){bflo(dw[2]), bfhi(dw[2]), bflo(dw[3]), bfhi(dw[3])};
;                 }
;                 const f32x4 x0 = cur[bj][0] + dl0, x1 = cur[bj][1] + dl1;
;                 if (dmode == 1) { u32x4 dw; dw.x = cvt_pk_bf16(dl0[0], dl0[1]); dw.y = cvt_pk_bf16(dl0[2], dl0[3]); dw.z = cvt_pk_bf16(dl1[0], dl1[1]); dw.w = cvt_pk_bf16(dl1[2], dl1[3]); *(u32x4*)dp = dw; }
.LBB0_677:
	s_lshl_b32 s34, s18, 8
	s_add_i32 s18, s34, 0xffff0000
	s_and_b64 s[4:5], exec, s[4:5]
	v_readlane_b32 s4, v254, 47
	s_cselect_b32 s5, s4, s27
	v_readlane_b32 s4, v254, 48
	s_cselect_b32 s18, s18, s34
	s_cselect_b32 s4, s4, s29
	s_lshl_b64 s[6:7], s[6:7], 2
	s_add_u32 s20, s31, s6
	v_lshl_or_b32 v200, s19, 8, v163
	s_addc_u32 s21, s58, s7
	v_ashrrev_i32_e32 v201, 31, v200
	v_lshlrev_b64 v[198:199], 2, v[200:201]
	s_add_u32 s6, s62, s6
	v_lshl_add_u64 v[182:183], s[20:21], 0, v[198:199]
	s_addc_u32 s7, s63, s7
	v_lshl_add_u64 v[184:185], s[48:49], 0, v[198:199]
	v_lshl_add_u64 v[202:203], s[6:7], 0, v[198:199]
	global_load_dwordx4 v[52:55], v[182:183], off offset:16
	global_load_dwordx4 v[56:59], v[182:183], off
	global_load_dwordx4 v[36:39], v[184:185], off offset:16
	global_load_dwordx4 v[40:43], v[184:185], off
	global_load_dwordx4 v[148:151], v[202:203], off offset:16
	global_load_dwordx4 v[152:155], v[202:203], off
	v_lshl_add_u64 v[198:199], s[4:5], 0, v[198:199]
	v_lshlrev_b64 v[200:201], 1, v[200:201]
	s_ashr_i32 s35, s34, 31
	s_waitcnt vmcnt(0)
	v_pk_mul_f32 v[236:237], v[140:141], v[52:53]
	v_pk_mul_f32 v[232:233], v[146:147], v[58:59]
	v_pk_mul_f32 v[230:231], v[144:145], v[56:57]
	v_pk_mul_f32 v[234:235], v[142:143], v[54:55]
	v_cvt_pk_bf16_f32 v230, v230, v231
	v_pk_add_f32 v[154:155], v[154:155], 1.0 op_sel_hi:[1,0]
	v_pk_add_f32 v[152:153], v[152:153], 1.0 op_sel_hi:[1,0]
	v_pk_mul_f32 v[190:191], v[42:43], v[154:155]
	v_pk_mul_f32 v[192:193], v[40:41], v[152:153]
	v_pk_add_f32 v[40:41], v[150:151], 1.0 op_sel_hi:[1,0]
	v_pk_add_f32 v[42:43], v[148:149], 1.0 op_sel_hi:[1,0]
	v_pk_mul_f32 v[194:195], v[38:39], v[40:41]
	v_pk_mul_f32 v[196:197], v[36:37], v[42:43]
	global_load_dwordx4 v[40:43], v[182:183], off offset:528
	global_load_dwordx4 v[36:39], v[182:183], off offset:512
	global_load_dwordx4 v[148:151], v[184:185], off offset:528
	global_load_dwordx4 v[152:155], v[184:185], off offset:512
	global_load_dwordx4 v[186:189], v[202:203], off offset:528
	s_nop 0
	global_load_dwordx4 v[182:185], v[202:203], off offset:512
	v_cvt_pk_bf16_f32 v231, v232, v233
	v_cvt_pk_bf16_f32 v232, v236, v237
	v_cvt_pk_bf16_f32 v233, v234, v235
	s_waitcnt vmcnt(0)
	v_pk_add_f32 v[184:185], v[184:185], 1.0 op_sel_hi:[1,0]
	v_pk_add_f32 v[202:203], v[182:183], 1.0 op_sel_hi:[1,0]
	v_pk_mul_f32 v[182:183], v[154:155], v[184:185]
	v_pk_add_f32 v[154:155], v[186:187], 1.0 op_sel_hi:[1,0]
	v_pk_mul_f32 v[184:185], v[152:153], v[202:203]
	v_pk_add_f32 v[152:153], v[188:189], 1.0 op_sel_hi:[1,0]
	v_pk_mul_f32 v[188:189], v[148:149], v[154:155]
	v_add_u32_e32 v148, s18, v162
	v_ashrrev_i32_e32 v149, 31, v148
	v_lshlrev_b64 v[148:149], 12, v[148:149]
	v_pk_mul_f32 v[186:187], v[150:151], v[152:153]
	v_lshl_add_u64 v[152:153], v[198:199], 0, v[148:149]
	global_load_dwordx4 v[214:217], v[152:153], off
	global_load_dwordx4 v[226:229], v[152:153], off offset:16
	global_load_dwordx4 v[148:151], v[152:153], off offset:512
	s_nop 0
	global_load_dwordx4 v[152:155], v[152:153], off offset:528
	v_add_u32_e32 v202, s34, v162
	v_ashrrev_i32_e32 v203, 31, v202
	v_lshlrev_b64 v[224:225], 11, v[202:203]
	v_lshl_add_u64 v[202:203], s[78:79], 0, v[224:225]
	v_lshl_add_u64 v[202:203], v[202:203], 0, v[200:201]
	global_store_dwordx4 v[202:203], v[230:233], off
	s_waitcnt vmcnt(4)
	v_pk_fma_f32 v[146:147], v[146:147], v[58:59], v[216:217]
	v_pk_fma_f32 v[144:145], v[144:145], v[56:57], v[214:215]
	v_mul_f32_e32 v215, v147, v147
	v_mul_f32_e32 v214, v145, v145
	s_waitcnt vmcnt(3)
	v_pk_fma_f32 v[140:141], v[140:141], v[52:53], v[226:227]
	v_fmac_f32_e32 v214, v144, v144
	v_fmac_f32_e32 v215, v146, v146
	v_add_f32_e32 v214, v214, v215
	v_mul_f32_e32 v215, v141, v141
	v_pk_fma_f32 v[142:143], v[142:143], v[54:55], v[228:229]
	v_fmac_f32_e32 v215, v140, v140
	v_add_f32_e32 v214, v214, v215
	v_mul_f32_e32 v215, v143, v143
	v_fmac_f32_e32 v215, v142, v142
	v_pk_mul_f32 v[144:145], v[192:193], v[144:145]
	v_add_f32_e32 v216, v215, v214
	v_pk_mul_f32 v[146:147], v[190:191], v[146:147]
	v_pk_mul_f32 v[214:215], v[194:195], v[142:143]
	v_pk_mul_f32 v[142:143], v[196:197], v[140:141]
	v_cvt_pk_bf16_f32 v140, v144, v145
	v_lshl_add_u64 v[144:145], s[64:65], 0, v[224:225]
	v_cvt_pk_bf16_f32 v141, v146, v147
	v_cvt_pk_bf16_f32 v142, v142, v143
	v_cvt_pk_bf16_f32 v143, v214, v215
	v_lshl_add_u64 v[144:145], v[144:145], 0, v[200:201]
	global_store_dwordx4 v[144:145], v[140:143], off
	v_pk_mul_f32 v[146:147], v[134:135], v[42:43]
	v_pk_mul_f32 v[214:215], v[132:133], v[40:41]
	v_pk_mul_f32 v[142:143], v[138:139], v[38:39]
	v_pk_mul_f32 v[140:141], v[136:137], v[36:37]
	s_waitcnt vmcnt(3)
	v_pk_fma_f32 v[138:139], v[138:139], v[38:39], v[150:151]
	v_cvt_pk_bf16_f32 v140, v140, v141
	v_cvt_pk_bf16_f32 v141, v142, v143
	v_cvt_pk_bf16_f32 v142, v214, v215
	v_cvt_pk_bf16_f32 v143, v146, v147
	global_store_dwordx4 v[202:203], v[140:143], off offset:256
	v_pk_fma_f32 v[136:137], v[136:137], v[36:37], v[148:149]
	s_waitcnt vmcnt(3)
	v_pk_fma_f32 v[140:141], v[134:135], v[42:43], v[154:155]
	v_pk_fma_f32 v[142:143], v[132:133], v[40:41], v[152:153]
	v_pk_mul_f32 v[134:135], v[182:183], v[138:139]
	v_pk_mul_f32 v[132:133], v[184:185], v[136:137]
	v_pk_mul_f32 v[146:147], v[186:187], v[140:141]
	v_pk_mul_f32 v[148:149], v[188:189], v[142:143]
	v_cvt_pk_bf16_f32 v132, v132, v133
	v_cvt_pk_bf16_f32 v133, v134, v135
	v_cvt_pk_bf16_f32 v134, v148, v149
	v_cvt_pk_bf16_f32 v135, v146, v147
	global_store_dwordx4 v[144:145], v[132:135], off offset:256
	s_nop 1
	v_mul_f32_e32 v133, v137, v137
	v_mul_f32_e32 v134, v139, v139
	v_fmac_f32_e32 v133, v136, v136
	v_fmac_f32_e32 v134, v138, v138
	v_add_f32_e32 v133, v133, v134
	v_mul_f32_e32 v134, v143, v143
	v_mul_f32_e32 v132, v141, v141
	v_fmac_f32_e32 v134, v142, v142
	v_fmac_f32_e32 v132, v140, v140
	v_add_f32_e32 v133, v133, v134
	v_and_b32_e32 v134, 64, v222
	v_add_f32_e32 v132, v132, v133
	v_xor_b32_e32 v133, 16, v222
	v_add_u32_e32 v134, 64, v134
	v_cmp_lt_i32_e32 vcc, v133, v134
	v_add_f32_e32 v132, v132, v216
	v_lshl_add_u64 v[140:141], s[34:35], 2, v[168:169]
	v_cndmask_b32_e32 v133, v222, v133, vcc
	v_lshlrev_b32_e32 v142, 2, v133
	ds_bpermute_b32 v133, v142, v132
	s_waitcnt lgkmcnt(0)
	v_add_f32_e32 v132, v132, v133
	v_xor_b32_e32 v133, 32, v222
	v_cmp_lt_i32_e32 vcc, v133, v134
	s_nop 1
	v_cndmask_b32_e32 v133, v222, v133, vcc
	v_lshlrev_b32_e32 v143, 2, v133
	ds_bpermute_b32 v133, v143, v132
	s_and_saveexec_b64 s[4:5], s[38:39]
	s_cbranch_execz .LBB0_679
	s_waitcnt lgkmcnt(0)
	v_add_f32_e32 v132, v132, v133
	v_mov_b32_e32 v244, v132
; __device__ __forceinline__ float bflo(unsigned w) { return __uint_as_float(w << 16); }
;     __device__ __forceinline__ void operator()(const pg8::f32x4 (&acc)[2][2][4][2], const pg8::Unit& u, int wr, int wc, int fr, int fq) const {
;     ...
;         for (int it = 0; it < 8; ++it) {
;             const int ai = it >> 2, m = it & 3;
;             const int rl = ai * 128 + wr * 64 + m * 16 + fr;
;             const size_t off = (size_t)(prow0 + rl) * DM + col0;
;             f32x4 cur[2][2];
; #pragma unroll
;             for (int bj = 0; bj < 2; ++bj) { cur[bj][0] = *(const f32x4*)(xin + off + bj * 128); cur[bj][1] = *(const f32x4*)(xin + off + bj * 128 + 4); }
;             float ss = 0.f;
; #pragma unroll
;             for (int bj = 0; bj < 2; ++bj) {
;                 f32x4 dl0 = gv[bj][0] * acc[ai][bj][m][0], dl1 = gv[bj][1] * acc[ai][bj][m][1];
;                 bf16* dp = d1 + (size_t)(u.pm * 256 + rl) * DM + col0 + bj * 128;
;                 if (dmode == 2) {
;                     const u32x4 dw = *(const u32x4*)dp;
;                     dl0 += (f32x4){bflo(dw[0]), bfhi(dw[0]), bflo(dw[1]), bfhi(dw[1])}; dl1 += (f32x4){bflo(dw[2]), bfhi(dw[2]), bflo(dw[3]), bfhi(dw[3])};
;                 }
;                 const f32x4 x0 = cur[bj][0] + dl0, x1 = cur[bj][1] + dl1;
;                 if (dmode == 1) { u32x4 dw; dw.x = cvt_pk_bf16(dl0[0], dl0[1]); dw.y = cvt_pk_bf16(dl0[2], dl0[3]); dw.z = cvt_pk_bf16(dl1[0], dl1[1]); dw.w = cvt_pk_bf16(dl1[2], dl1[3]); *(u32x4*)dp = dw; }
;                 else { *(f32x4*)(xout + off + bj * 128) = x0; *(f32x4*)(xout + off + bj * 128 + 4) = x1; }
;                 if (has_next) {
;                     ss += (x0[0] * x0[0] + x0[1] * x0[1]) + (x0[2] * x0[2] + x0[3] * x0[3]) + (x1[0] * x1[0] + x1[1] * x1[1]) + (x1[2] * x1[2] + x1[3] * x1[3]);
;                     const f32x4 y0 = x0 * gm[bj][0], y1 = x1 * gm[bj][1];
;                     u32x4 w; w.x = cvt_pk_bf16(y0[0], y0[1]); w.y = cvt_pk_bf16(y0[2], y0[3]); w.z = cvt_pk_bf16(y1[0], y1[1]); w.w = cvt_pk_bf16(y1[2], y1[3]);
;                     *(u32x4*)(xb + (size_t)(u.pm * 256 + rl) * DM + col0 + bj * 128) = w;
;                 }
;             }
;             if (has_next) {
;                 ss += __shfl_xor(ss, 16); ss += __shfl_xor(ss, 32);
;                 if (fq == 0) atomicAdd(rowss_next + u.pm * 256 + rl, ss);
.LBB0_679:
	s_or_b64 exec, exec, s[4:5]
	v_add_u32_e32 v132, s18, v204
	s_waitcnt lgkmcnt(0)
	v_ashrrev_i32_e32 v133, 31, v132
	v_lshlrev_b64 v[132:133], 12, v[132:133]
	v_lshl_add_u64 v[136:137], v[198:199], 0, v[132:133]
	global_load_dwordx4 v[144:147], v[136:137], off
	global_load_dwordx4 v[148:151], v[136:137], off offset:16
	global_load_dwordx4 v[132:135], v[136:137], off offset:512
	s_nop 0
	global_load_dwordx4 v[136:139], v[136:137], off offset:528
	v_add_u32_e32 v152, s34, v204
	v_ashrrev_i32_e32 v153, 31, v152
	v_lshlrev_b64 v[202:203], 11, v[152:153]
	v_pk_mul_f32 v[154:155], v[130:131], v[58:59]
	v_pk_mul_f32 v[152:153], v[128:129], v[56:57]
	v_pk_mul_f32 v[216:217], v[124:125], v[52:53]
	v_pk_mul_f32 v[214:215], v[126:127], v[54:55]
	v_lshl_add_u64 v[224:225], s[78:79], 0, v[202:203]
	v_lshl_add_u64 v[224:225], v[224:225], 0, v[200:201]
	v_cvt_pk_bf16_f32 v152, v152, v153
	v_cvt_pk_bf16_f32 v153, v154, v155
	v_cvt_pk_bf16_f32 v154, v216, v217
	v_cvt_pk_bf16_f32 v155, v214, v215
	global_store_dwordx4 v[224:225], v[152:155], off
	s_waitcnt vmcnt(4)
	v_pk_fma_f32 v[130:131], v[130:131], v[58:59], v[146:147]
	v_pk_fma_f32 v[128:129], v[128:129], v[56:57], v[144:145]
	v_mul_f32_e32 v145, v131, v131
	v_mul_f32_e32 v144, v129, v129
	s_waitcnt vmcnt(3)
	v_pk_fma_f32 v[124:125], v[124:125], v[52:53], v[148:149]
	v_fmac_f32_e32 v144, v128, v128
	v_fmac_f32_e32 v145, v130, v130
	v_add_f32_e32 v144, v144, v145
	v_mul_f32_e32 v145, v125, v125
	v_pk_fma_f32 v[126:127], v[126:127], v[54:55], v[150:151]
	v_fmac_f32_e32 v145, v124, v124
	v_add_f32_e32 v144, v144, v145
	v_mul_f32_e32 v145, v127, v127
	v_fmac_f32_e32 v145, v126, v126
	v_pk_mul_f32 v[128:129], v[192:193], v[128:129]
	v_pk_mul_f32 v[124:125], v[196:197], v[124:125]
	v_add_f32_e32 v146, v145, v144
	v_pk_mul_f32 v[130:131], v[190:191], v[130:131]
	v_pk_mul_f32 v[144:145], v[194:195], v[126:127]
	v_cvt_pk_bf16_f32 v126, v128, v129
	v_cvt_pk_bf16_f32 v128, v124, v125
	v_lshl_add_u64 v[124:125], s[64:65], 0, v[202:203]
	v_cvt_pk_bf16_f32 v127, v130, v131
	v_cvt_pk_bf16_f32 v129, v144, v145
	v_lshl_add_u64 v[124:125], v[124:125], 0, v[200:201]
	global_store_dwordx4 v[124:125], v[126:129], off
	v_pk_mul_f32 v[130:131], v[118:119], v[42:43]
	v_pk_mul_f32 v[144:145], v[116:117], v[40:41]
	v_pk_mul_f32 v[128:129], v[122:123], v[38:39]
	v_pk_mul_f32 v[126:127], v[120:121], v[36:37]
	s_waitcnt vmcnt(3)
	v_pk_fma_f32 v[122:123], v[122:123], v[38:39], v[134:135]
	v_cvt_pk_bf16_f32 v126, v126, v127
	v_cvt_pk_bf16_f32 v127, v128, v129
	v_cvt_pk_bf16_f32 v128, v144, v145
	v_cvt_pk_bf16_f32 v129, v130, v131
	global_store_dwordx4 v[224:225], v[126:129], off offset:256
	v_pk_fma_f32 v[120:121], v[120:121], v[36:37], v[132:133]
	s_waitcnt vmcnt(3)
	v_pk_fma_f32 v[126:127], v[118:119], v[42:43], v[138:139]
	v_pk_fma_f32 v[128:129], v[116:117], v[40:41], v[136:137]
	v_pk_mul_f32 v[118:119], v[182:183], v[122:123]
	v_pk_mul_f32 v[116:117], v[184:185], v[120:121]
	v_pk_mul_f32 v[130:131], v[186:187], v[126:127]
	v_pk_mul_f32 v[132:133], v[188:189], v[128:129]
	v_cvt_pk_bf16_f32 v116, v116, v117
	v_cvt_pk_bf16_f32 v117, v118, v119
	v_cvt_pk_bf16_f32 v118, v132, v133
	v_cvt_pk_bf16_f32 v119, v130, v131
	global_store_dwordx4 v[124:125], v[116:119], off offset:256
	s_nop 1
	v_mul_f32_e32 v117, v121, v121
	v_mul_f32_e32 v118, v123, v123
	v_fmac_f32_e32 v117, v120, v120
	v_fmac_f32_e32 v118, v122, v122
	v_add_f32_e32 v117, v117, v118
	v_mul_f32_e32 v118, v129, v129
	v_mul_f32_e32 v116, v127, v127
	v_fmac_f32_e32 v118, v128, v128
	v_fmac_f32_e32 v116, v126, v126
	v_add_f32_e32 v117, v117, v118
	v_add_f32_e32 v116, v116, v117
	v_add_f32_e32 v116, v116, v146
	ds_bpermute_b32 v117, v142, v116
	s_waitcnt lgkmcnt(0)
	v_add_f32_e32 v116, v116, v117
	ds_bpermute_b32 v117, v143, v116
	s_and_saveexec_b64 s[4:5], s[38:39]
	s_cbranch_execz .LBB0_681
	s_waitcnt lgkmcnt(0)
	v_add_f32_e32 v116, v116, v117
	v_mov_b32_e32 v245, v116
.LBB0_681:
	s_or_b64 exec, exec, s[4:5]
	v_add_u32_e32 v116, s18, v205
	s_waitcnt lgkmcnt(0)
	v_ashrrev_i32_e32 v117, 31, v116
	v_lshlrev_b64 v[116:117], 12, v[116:117]
	v_lshl_add_u64 v[120:121], v[198:199], 0, v[116:117]
	global_load_dwordx4 v[124:127], v[120:121], off
	global_load_dwordx4 v[128:131], v[120:121], off offset:16
	global_load_dwordx4 v[116:119], v[120:121], off offset:512
	s_nop 0
	global_load_dwordx4 v[120:123], v[120:121], off offset:528
	v_add_u32_e32 v132, s34, v205
	v_ashrrev_i32_e32 v133, 31, v132
	v_lshlrev_b64 v[136:137], 11, v[132:133]
	v_pk_mul_f32 v[134:135], v[114:115], v[58:59]
	v_pk_mul_f32 v[132:133], v[112:113], v[56:57]
	v_pk_mul_f32 v[144:145], v[108:109], v[52:53]
	v_pk_mul_f32 v[138:139], v[110:111], v[54:55]
	v_lshl_add_u64 v[146:147], s[78:79], 0, v[136:137]
	v_lshl_add_u64 v[146:147], v[146:147], 0, v[200:201]
	v_cvt_pk_bf16_f32 v132, v132, v133
	v_cvt_pk_bf16_f32 v133, v134, v135
	v_cvt_pk_bf16_f32 v134, v144, v145
	v_cvt_pk_bf16_f32 v135, v138, v139
	global_store_dwordx4 v[146:147], v[132:135], off
	s_waitcnt vmcnt(4)
	v_pk_fma_f32 v[114:115], v[114:115], v[58:59], v[126:127]
	v_pk_fma_f32 v[112:113], v[112:113], v[56:57], v[124:125]
	v_mul_f32_e32 v125, v115, v115
	v_mul_f32_e32 v124, v113, v113
	s_waitcnt vmcnt(3)
; __device__ __forceinline__ float bflo(unsigned w) { return __uint_as_float(w << 16); }
;     __device__ __forceinline__ void operator()(const pg8::f32x4 (&acc)[2][2][4][2], const pg8::Unit& u, int wr, int wc, int fr, int fq) const {
;     ...
;         for (int it = 0; it < 8; ++it) {
;             const int ai = it >> 2, m = it & 3;
;             const int rl = ai * 128 + wr * 64 + m * 16 + fr;
;             const size_t off = (size_t)(prow0 + rl) * DM + col0;
;             f32x4 cur[2][2];
; #pragma unroll
;             for (int bj = 0; bj < 2; ++bj) { cur[bj][0] = *(const f32x4*)(xin + off + bj * 128); cur[bj][1] = *(const f32x4*)(xin + off + bj * 128 + 4); }
;             float ss = 0.f;
; #pragma unroll
;             for (int bj = 0; bj < 2; ++bj) {
;                 f32x4 dl0 = gv[bj][0] * acc[ai][bj][m][0], dl1 = gv[bj][1] * acc[ai][bj][m][1];
;                 bf16* dp = d1 + (size_t)(u.pm * 256 + rl) * DM + col0 + bj * 128;
;                 if (dmode == 2) {
;                     const u32x4 dw = *(const u32x4*)dp;
;                     dl0 += (f32x4){bflo(dw[0]), bfhi(dw[0]), bflo(dw[1]), bfhi(dw[1])}; dl1 += (f32x4){bflo(dw[2]), bfhi(dw[2]), bflo(dw[3]), bfhi(dw[3])};
;                 }
;                 const f32x4 x0 = cur[bj][0] + dl0, x1 = cur[bj][1] + dl1;
;                 if (dmode == 1) { u32x4 dw; dw.x = cvt_pk_bf16(dl0[0], dl0[1]); dw.y = cvt_pk_bf16(dl0[2], dl0[3]); dw.z = cvt_pk_bf16(dl1[0], dl1[1]); dw.w = cvt_pk_bf16(dl1[2], dl1[3]); *(u32x4*)dp = dw; }
;                 else { *(f32x4*)(xout + off + bj * 128) = x0; *(f32x4*)(xout + off + bj * 128 + 4) = x1; }
;                 if (has_next) {
;                     ss += (x0[0] * x0[0] + x0[1] * x0[1]) + (x0[2] * x0[2] + x0[3] * x0[3]) + (x1[0] * x1[0] + x1[1] * x1[1]) + (x1[2] * x1[2] + x1[3] * x1[3]);
;                     const f32x4 y0 = x0 * gm[bj][0], y1 = x1 * gm[bj][1];
;                     u32x4 w; w.x = cvt_pk_bf16(y0[0], y0[1]); w.y = cvt_pk_bf16(y0[2], y0[3]); w.z = cvt_pk_bf16(y1[0], y1[1]); w.w = cvt_pk_bf16(y1[2], y1[3]);
;                     *(u32x4*)(xb + (size_t)(u.pm * 256 + rl) * DM + col0 + bj * 128) = w;
;                 }
;             }
;             if (has_next) {
;                 ss += __shfl_xor(ss, 16); ss += __shfl_xor(ss, 32);
;                 if (fq == 0) atomicAdd(rowss_next + u.pm * 256 + rl, ss);
	v_pk_fma_f32 v[108:109], v[108:109], v[52:53], v[128:129]
	v_fmac_f32_e32 v124, v112, v112
	v_fmac_f32_e32 v125, v114, v114
	v_add_f32_e32 v124, v124, v125
	v_mul_f32_e32 v125, v109, v109
	v_pk_fma_f32 v[110:111], v[110:111], v[54:55], v[130:131]
	v_fmac_f32_e32 v125, v108, v108
	v_add_f32_e32 v124, v124, v125
	v_mul_f32_e32 v125, v111, v111
	v_fmac_f32_e32 v125, v110, v110
	v_pk_mul_f32 v[112:113], v[192:193], v[112:113]
	v_pk_mul_f32 v[108:109], v[196:197], v[108:109]
	v_add_f32_e32 v126, v125, v124
	v_pk_mul_f32 v[114:115], v[190:191], v[114:115]
	v_pk_mul_f32 v[124:125], v[194:195], v[110:111]
	v_cvt_pk_bf16_f32 v110, v112, v113
	v_cvt_pk_bf16_f32 v112, v108, v109
	v_lshl_add_u64 v[108:109], s[64:65], 0, v[136:137]
	v_cvt_pk_bf16_f32 v111, v114, v115
	v_cvt_pk_bf16_f32 v113, v124, v125
	v_lshl_add_u64 v[108:109], v[108:109], 0, v[200:201]
	global_store_dwordx4 v[108:109], v[110:113], off
	v_pk_mul_f32 v[114:115], v[102:103], v[42:43]
	v_pk_mul_f32 v[124:125], v[100:101], v[40:41]
	v_pk_mul_f32 v[112:113], v[106:107], v[38:39]
	v_pk_mul_f32 v[110:111], v[104:105], v[36:37]
	s_waitcnt vmcnt(3)
	v_pk_fma_f32 v[106:107], v[106:107], v[38:39], v[118:119]
	v_cvt_pk_bf16_f32 v110, v110, v111
	v_cvt_pk_bf16_f32 v111, v112, v113
	v_cvt_pk_bf16_f32 v112, v124, v125
	v_cvt_pk_bf16_f32 v113, v114, v115
	global_store_dwordx4 v[146:147], v[110:113], off offset:256
	v_pk_fma_f32 v[104:105], v[104:105], v[36:37], v[116:117]
	s_waitcnt vmcnt(3)
	v_pk_fma_f32 v[110:111], v[102:103], v[42:43], v[122:123]
	v_pk_fma_f32 v[112:113], v[100:101], v[40:41], v[120:121]
	v_pk_mul_f32 v[102:103], v[182:183], v[106:107]
	v_pk_mul_f32 v[100:101], v[184:185], v[104:105]
	v_pk_mul_f32 v[114:115], v[186:187], v[110:111]
	v_pk_mul_f32 v[116:117], v[188:189], v[112:113]
	v_cvt_pk_bf16_f32 v100, v100, v101
	v_cvt_pk_bf16_f32 v101, v102, v103
	v_cvt_pk_bf16_f32 v102, v116, v117
	v_cvt_pk_bf16_f32 v103, v114, v115
	global_store_dwordx4 v[108:109], v[100:103], off offset:256
	s_nop 1
	v_mul_f32_e32 v101, v105, v105
	v_mul_f32_e32 v102, v107, v107
	v_fmac_f32_e32 v101, v104, v104
	v_fmac_f32_e32 v102, v106, v106
	v_add_f32_e32 v101, v101, v102
	v_mul_f32_e32 v102, v113, v113
	v_mul_f32_e32 v100, v111, v111
	v_fmac_f32_e32 v102, v112, v112
	v_fmac_f32_e32 v100, v110, v110
	v_add_f32_e32 v101, v101, v102
	v_add_f32_e32 v100, v100, v101
	v_add_f32_e32 v100, v100, v126
	ds_bpermute_b32 v101, v142, v100
	s_waitcnt lgkmcnt(0)
	v_add_f32_e32 v100, v100, v101
	ds_bpermute_b32 v101, v143, v100
	s_and_saveexec_b64 s[4:5], s[38:39]
	s_cbranch_execz .LBB0_683
	s_waitcnt lgkmcnt(0)
	v_add_f32_e32 v100, v100, v101
	v_mov_b32_e32 v246, v100
.LBB0_683:
	s_or_b64 exec, exec, s[4:5]
	v_add_u32_e32 v100, s18, v206
	s_waitcnt lgkmcnt(0)
	v_ashrrev_i32_e32 v101, 31, v100
	v_lshlrev_b64 v[100:101], 12, v[100:101]
	v_lshl_add_u64 v[104:105], v[198:199], 0, v[100:101]
	global_load_dwordx4 v[108:111], v[104:105], off
	global_load_dwordx4 v[112:115], v[104:105], off offset:16
	global_load_dwordx4 v[100:103], v[104:105], off offset:512
	s_nop 0
	global_load_dwordx4 v[104:107], v[104:105], off offset:528
	v_add_u32_e32 v116, s34, v206
	v_ashrrev_i32_e32 v117, 31, v116
	v_lshlrev_b64 v[120:121], 11, v[116:117]
	v_pk_mul_f32 v[118:119], v[98:99], v[58:59]
	v_pk_mul_f32 v[116:117], v[96:97], v[56:57]
	v_pk_mul_f32 v[124:125], v[92:93], v[52:53]
	v_pk_mul_f32 v[122:123], v[94:95], v[54:55]
	v_lshl_add_u64 v[126:127], s[78:79], 0, v[120:121]
	v_lshl_add_u64 v[126:127], v[126:127], 0, v[200:201]
	v_cvt_pk_bf16_f32 v116, v116, v117
	v_cvt_pk_bf16_f32 v117, v118, v119
	v_cvt_pk_bf16_f32 v118, v124, v125
	v_cvt_pk_bf16_f32 v119, v122, v123
	global_store_dwordx4 v[126:127], v[116:119], off
	s_waitcnt vmcnt(4)
	v_pk_fma_f32 v[98:99], v[98:99], v[58:59], v[110:111]
	v_pk_fma_f32 v[96:97], v[96:97], v[56:57], v[108:109]
	v_mul_f32_e32 v109, v99, v99
	v_mul_f32_e32 v108, v97, v97
	s_waitcnt vmcnt(3)
	v_pk_fma_f32 v[92:93], v[92:93], v[52:53], v[112:113]
	v_fmac_f32_e32 v108, v96, v96
	v_fmac_f32_e32 v109, v98, v98
	v_add_f32_e32 v108, v108, v109
	v_mul_f32_e32 v109, v93, v93
	v_pk_fma_f32 v[94:95], v[94:95], v[54:55], v[114:115]
	v_fmac_f32_e32 v109, v92, v92
	v_add_f32_e32 v108, v108, v109
	v_mul_f32_e32 v109, v95, v95
	v_fmac_f32_e32 v109, v94, v94
	v_pk_mul_f32 v[96:97], v[192:193], v[96:97]
	v_pk_mul_f32 v[92:93], v[196:197], v[92:93]
	v_add_f32_e32 v110, v109, v108
	v_pk_mul_f32 v[98:99], v[190:191], v[98:99]
	v_pk_mul_f32 v[108:109], v[194:195], v[94:95]
	v_cvt_pk_bf16_f32 v94, v96, v97
	v_cvt_pk_bf16_f32 v96, v92, v93
	v_lshl_add_u64 v[92:93], s[64:65], 0, v[120:121]
	v_cvt_pk_bf16_f32 v95, v98, v99
	v_cvt_pk_bf16_f32 v97, v108, v109
	v_lshl_add_u64 v[92:93], v[92:93], 0, v[200:201]
	global_store_dwordx4 v[92:93], v[94:97], off
	v_pk_mul_f32 v[98:99], v[86:87], v[42:43]
	v_pk_mul_f32 v[108:109], v[84:85], v[40:41]
	v_pk_mul_f32 v[96:97], v[90:91], v[38:39]
	v_pk_mul_f32 v[94:95], v[88:89], v[36:37]
	s_waitcnt vmcnt(3)
	v_pk_fma_f32 v[90:91], v[90:91], v[38:39], v[102:103]
	v_cvt_pk_bf16_f32 v94, v94, v95
	v_cvt_pk_bf16_f32 v95, v96, v97
	v_cvt_pk_bf16_f32 v96, v108, v109
	v_cvt_pk_bf16_f32 v97, v98, v99
	global_store_dwordx4 v[126:127], v[94:97], off offset:256
	v_pk_fma_f32 v[88:89], v[88:89], v[36:37], v[100:101]
	s_waitcnt vmcnt(3)
	v_pk_fma_f32 v[94:95], v[86:87], v[42:43], v[106:107]
	v_pk_fma_f32 v[96:97], v[84:85], v[40:41], v[104:105]
	v_pk_mul_f32 v[86:87], v[182:183], v[90:91]
	v_pk_mul_f32 v[84:85], v[184:185], v[88:89]
	v_pk_mul_f32 v[98:99], v[186:187], v[94:95]
	v_pk_mul_f32 v[100:101], v[188:189], v[96:97]
	v_cvt_pk_bf16_f32 v84, v84, v85
	v_cvt_pk_bf16_f32 v85, v86, v87
	v_cvt_pk_bf16_f32 v86, v100, v101
	v_cvt_pk_bf16_f32 v87, v98, v99
	global_store_dwordx4 v[92:93], v[84:87], off offset:256
	s_nop 1
	v_mul_f32_e32 v85, v89, v89
	v_mul_f32_e32 v86, v91, v91
	v_fmac_f32_e32 v85, v88, v88
	v_fmac_f32_e32 v86, v90, v90
	v_add_f32_e32 v85, v85, v86
	v_mul_f32_e32 v86, v97, v97
	v_mul_f32_e32 v84, v95, v95
	v_fmac_f32_e32 v86, v96, v96
	v_fmac_f32_e32 v84, v94, v94
	v_add_f32_e32 v85, v85, v86
	v_add_f32_e32 v84, v84, v85
	v_add_f32_e32 v84, v84, v110
	ds_bpermute_b32 v85, v142, v84
	s_waitcnt lgkmcnt(0)
	v_add_f32_e32 v84, v84, v85
	ds_bpermute_b32 v85, v143, v84
	s_and_saveexec_b64 s[4:5], s[38:39]
	s_cbranch_execz .LBB0_685
	s_waitcnt lgkmcnt(0)
	v_add_f32_e32 v84, v84, v85
	v_mov_b32_e32 v247, v84
; __device__ __forceinline__ float bflo(unsigned w) { return __uint_as_float(w << 16); }
;     __device__ __forceinline__ void operator()(const pg8::f32x4 (&acc)[2][2][4][2], const pg8::Unit& u, int wr, int wc, int fr, int fq) const {
;     ...
;         for (int it = 0; it < 8; ++it) {
;             const int ai = it >> 2, m = it & 3;
;             const int rl = ai * 128 + wr * 64 + m * 16 + fr;
;             const size_t off = (size_t)(prow0 + rl) * DM + col0;
;             f32x4 cur[2][2];
; #pragma unroll
;             for (int bj = 0; bj < 2; ++bj) { cur[bj][0] = *(const f32x4*)(xin + off + bj * 128); cur[bj][1] = *(const f32x4*)(xin + off + bj * 128 + 4); }
;             float ss = 0.f;
; #pragma unroll
;             for (int bj = 0; bj < 2; ++bj) {
;                 f32x4 dl0 = gv[bj][0] * acc[ai][bj][m][0], dl1 = gv[bj][1] * acc[ai][bj][m][1];
;                 bf16* dp = d1 + (size_t)(u.pm * 256 + rl) * DM + col0 + bj * 128;
;                 if (dmode == 2) {
;                     const u32x4 dw = *(const u32x4*)dp;
;                     dl0 += (f32x4){bflo(dw[0]), bfhi(dw[0]), bflo(dw[1]), bfhi(dw[1])}; dl1 += (f32x4){bflo(dw[2]), bfhi(dw[2]), bflo(dw[3]), bfhi(dw[3])};
;                 }
;                 const f32x4 x0 = cur[bj][0] + dl0, x1 = cur[bj][1] + dl1;
;                 if (dmode == 1) { u32x4 dw; dw.x = cvt_pk_bf16(dl0[0], dl0[1]); dw.y = cvt_pk_bf16(dl0[2], dl0[3]); dw.z = cvt_pk_bf16(dl1[0], dl1[1]); dw.w = cvt_pk_bf16(dl1[2], dl1[3]); *(u32x4*)dp = dw; }
;                 else { *(f32x4*)(xout + off + bj * 128) = x0; *(f32x4*)(xout + off + bj * 128 + 4) = x1; }
;                 if (has_next) {
;                     ss += (x0[0] * x0[0] + x0[1] * x0[1]) + (x0[2] * x0[2] + x0[3] * x0[3]) + (x1[0] * x1[0] + x1[1] * x1[1]) + (x1[2] * x1[2] + x1[3] * x1[3]);
;                     const f32x4 y0 = x0 * gm[bj][0], y1 = x1 * gm[bj][1];
;                     u32x4 w; w.x = cvt_pk_bf16(y0[0], y0[1]); w.y = cvt_pk_bf16(y0[2], y0[3]); w.z = cvt_pk_bf16(y1[0], y1[1]); w.w = cvt_pk_bf16(y1[2], y1[3]);
;                     *(u32x4*)(xb + (size_t)(u.pm * 256 + rl) * DM + col0 + bj * 128) = w;
;                 }
;             }
;             if (has_next) {
;                 ss += __shfl_xor(ss, 16); ss += __shfl_xor(ss, 32);
;                 if (fq == 0) atomicAdd(rowss_next + u.pm * 256 + rl, ss);
.LBB0_685:
	s_or_b64 exec, exec, s[4:5]
	v_add_u32_e32 v84, s18, v207
	s_waitcnt lgkmcnt(0)
	v_ashrrev_i32_e32 v85, 31, v84
	v_lshlrev_b64 v[84:85], 12, v[84:85]
	v_lshl_add_u64 v[88:89], v[198:199], 0, v[84:85]
	global_load_dwordx4 v[92:95], v[88:89], off
	global_load_dwordx4 v[96:99], v[88:89], off offset:16
	global_load_dwordx4 v[84:87], v[88:89], off offset:512
	s_nop 0
	global_load_dwordx4 v[88:91], v[88:89], off offset:528
	v_add_u32_e32 v100, s34, v207
	v_ashrrev_i32_e32 v101, 31, v100
	v_lshlrev_b64 v[104:105], 11, v[100:101]
	v_pk_mul_f32 v[102:103], v[82:83], v[58:59]
	v_pk_mul_f32 v[100:101], v[80:81], v[56:57]
	v_pk_mul_f32 v[108:109], v[76:77], v[52:53]
	v_pk_mul_f32 v[106:107], v[78:79], v[54:55]
	v_lshl_add_u64 v[110:111], s[78:79], 0, v[104:105]
	v_lshl_add_u64 v[110:111], v[110:111], 0, v[200:201]
	v_cvt_pk_bf16_f32 v100, v100, v101
	v_cvt_pk_bf16_f32 v101, v102, v103
	v_cvt_pk_bf16_f32 v102, v108, v109
	v_cvt_pk_bf16_f32 v103, v106, v107
	global_store_dwordx4 v[110:111], v[100:103], off
	s_waitcnt vmcnt(4)
	v_pk_fma_f32 v[82:83], v[82:83], v[58:59], v[94:95]
	v_pk_fma_f32 v[80:81], v[80:81], v[56:57], v[92:93]
	v_mul_f32_e32 v93, v83, v83
	v_mul_f32_e32 v92, v81, v81
	s_waitcnt vmcnt(3)
	v_pk_fma_f32 v[76:77], v[76:77], v[52:53], v[96:97]
	v_fmac_f32_e32 v92, v80, v80
	v_fmac_f32_e32 v93, v82, v82
	v_add_f32_e32 v92, v92, v93
	v_mul_f32_e32 v93, v77, v77
	v_pk_fma_f32 v[78:79], v[78:79], v[54:55], v[98:99]
	v_fmac_f32_e32 v93, v76, v76
	v_add_f32_e32 v92, v92, v93
	v_mul_f32_e32 v93, v79, v79
	v_fmac_f32_e32 v93, v78, v78
	v_pk_mul_f32 v[80:81], v[192:193], v[80:81]
	v_pk_mul_f32 v[76:77], v[196:197], v[76:77]
	v_add_f32_e32 v94, v93, v92
	v_pk_mul_f32 v[82:83], v[190:191], v[82:83]
	v_pk_mul_f32 v[92:93], v[194:195], v[78:79]
	v_cvt_pk_bf16_f32 v78, v80, v81
	v_cvt_pk_bf16_f32 v80, v76, v77
	v_lshl_add_u64 v[76:77], s[64:65], 0, v[104:105]
	v_cvt_pk_bf16_f32 v79, v82, v83
	v_cvt_pk_bf16_f32 v81, v92, v93
	v_lshl_add_u64 v[76:77], v[76:77], 0, v[200:201]
	global_store_dwordx4 v[76:77], v[78:81], off
	v_pk_mul_f32 v[82:83], v[70:71], v[42:43]
	v_pk_mul_f32 v[92:93], v[68:69], v[40:41]
	v_pk_mul_f32 v[80:81], v[74:75], v[38:39]
	v_pk_mul_f32 v[78:79], v[72:73], v[36:37]
	s_waitcnt vmcnt(3)
	v_pk_fma_f32 v[74:75], v[74:75], v[38:39], v[86:87]
	v_cvt_pk_bf16_f32 v78, v78, v79
	v_cvt_pk_bf16_f32 v79, v80, v81
	v_cvt_pk_bf16_f32 v80, v92, v93
	v_cvt_pk_bf16_f32 v81, v82, v83
	global_store_dwordx4 v[110:111], v[78:81], off offset:256
	v_pk_fma_f32 v[72:73], v[72:73], v[36:37], v[84:85]
	s_waitcnt vmcnt(3)
	v_pk_fma_f32 v[78:79], v[70:71], v[42:43], v[90:91]
	v_pk_fma_f32 v[80:81], v[68:69], v[40:41], v[88:89]
	v_pk_mul_f32 v[70:71], v[182:183], v[74:75]
	v_pk_mul_f32 v[68:69], v[184:185], v[72:73]
	v_pk_mul_f32 v[82:83], v[186:187], v[78:79]
	v_pk_mul_f32 v[84:85], v[188:189], v[80:81]
	v_cvt_pk_bf16_f32 v68, v68, v69
	v_cvt_pk_bf16_f32 v69, v70, v71
	v_cvt_pk_bf16_f32 v70, v84, v85
	v_cvt_pk_bf16_f32 v71, v82, v83
	global_store_dwordx4 v[76:77], v[68:71], off offset:256
	s_nop 1
	v_mul_f32_e32 v69, v73, v73
	v_mul_f32_e32 v70, v75, v75
	v_fmac_f32_e32 v69, v72, v72
	v_fmac_f32_e32 v70, v74, v74
	v_add_f32_e32 v69, v69, v70
	v_mul_f32_e32 v70, v81, v81
	v_mul_f32_e32 v68, v79, v79
	v_fmac_f32_e32 v70, v80, v80
	v_fmac_f32_e32 v68, v78, v78
	v_add_f32_e32 v69, v69, v70
	v_add_f32_e32 v68, v68, v69
	v_add_f32_e32 v68, v68, v94
	ds_bpermute_b32 v69, v142, v68
	s_waitcnt lgkmcnt(0)
	v_add_f32_e32 v68, v68, v69
	ds_bpermute_b32 v69, v143, v68
	s_and_saveexec_b64 s[4:5], s[38:39]
	s_cbranch_execz .LBB0_687
	v_lshl_add_u64 v[70:71], s[34:35], 2, v[170:171]
	s_waitcnt lgkmcnt(0)
	v_add_f32_e32 v68, v68, v69
	v_mov_b32_e32 v248, v68
.LBB0_687:
	s_or_b64 exec, exec, s[4:5]
	v_add_u32_e32 v68, s18, v208
	s_waitcnt lgkmcnt(0)
	v_ashrrev_i32_e32 v69, 31, v68
	v_lshlrev_b64 v[68:69], 12, v[68:69]
	v_lshl_add_u64 v[72:73], v[198:199], 0, v[68:69]
	global_load_dwordx4 v[76:79], v[72:73], off
	global_load_dwordx4 v[80:83], v[72:73], off offset:16
	global_load_dwordx4 v[68:71], v[72:73], off offset:512
	s_nop 0
	global_load_dwordx4 v[72:75], v[72:73], off offset:528
	v_add_u32_e32 v84, s34, v208
	v_ashrrev_i32_e32 v85, 31, v84
	v_lshlrev_b64 v[88:89], 11, v[84:85]
	v_pk_mul_f32 v[86:87], v[66:67], v[58:59]
	v_pk_mul_f32 v[84:85], v[64:65], v[56:57]
	v_pk_mul_f32 v[92:93], v[60:61], v[52:53]
	v_pk_mul_f32 v[90:91], v[62:63], v[54:55]
	v_lshl_add_u64 v[94:95], s[78:79], 0, v[88:89]
	v_lshl_add_u64 v[94:95], v[94:95], 0, v[200:201]
	v_cvt_pk_bf16_f32 v84, v84, v85
	v_cvt_pk_bf16_f32 v85, v86, v87
	v_cvt_pk_bf16_f32 v86, v92, v93
	v_cvt_pk_bf16_f32 v87, v90, v91
	global_store_dwordx4 v[94:95], v[84:87], off
	s_waitcnt vmcnt(4)
	v_pk_fma_f32 v[66:67], v[66:67], v[58:59], v[78:79]
	v_pk_fma_f32 v[64:65], v[64:65], v[56:57], v[76:77]
	v_mul_f32_e32 v77, v67, v67
	v_mul_f32_e32 v76, v65, v65
	s_waitcnt vmcnt(3)
	v_pk_fma_f32 v[60:61], v[60:61], v[52:53], v[80:81]
	v_fmac_f32_e32 v76, v64, v64
	v_fmac_f32_e32 v77, v66, v66
	v_add_f32_e32 v76, v76, v77
	v_mul_f32_e32 v77, v61, v61
	v_pk_fma_f32 v[62:63], v[62:63], v[54:55], v[82:83]
	v_fmac_f32_e32 v77, v60, v60
	v_add_f32_e32 v76, v76, v77
	v_mul_f32_e32 v77, v63, v63
	v_fmac_f32_e32 v77, v62, v62
	v_pk_mul_f32 v[64:65], v[192:193], v[64:65]
	v_pk_mul_f32 v[60:61], v[196:197], v[60:61]
	v_add_f32_e32 v78, v77, v76
	v_pk_mul_f32 v[66:67], v[190:191], v[66:67]
	v_pk_mul_f32 v[76:77], v[194:195], v[62:63]
	v_cvt_pk_bf16_f32 v62, v64, v65
	v_cvt_pk_bf16_f32 v64, v60, v61
	v_lshl_add_u64 v[60:61], s[64:65], 0, v[88:89]
	v_cvt_pk_bf16_f32 v63, v66, v67
	v_cvt_pk_bf16_f32 v65, v76, v77
	v_lshl_add_u64 v[60:61], v[60:61], 0, v[200:201]
	global_store_dwordx4 v[60:61], v[62:65], off
	v_pk_mul_f32 v[66:67], v[46:47], v[42:43]
	v_pk_mul_f32 v[76:77], v[44:45], v[40:41]
	v_pk_mul_f32 v[64:65], v[50:51], v[38:39]
	v_pk_mul_f32 v[62:63], v[48:49], v[36:37]
	s_waitcnt vmcnt(3)
; __device__ __forceinline__ float bflo(unsigned w) { return __uint_as_float(w << 16); }
;     __device__ __forceinline__ void operator()(const pg8::f32x4 (&acc)[2][2][4][2], const pg8::Unit& u, int wr, int wc, int fr, int fq) const {
;     ...
;         for (int it = 0; it < 8; ++it) {
;             const int ai = it >> 2, m = it & 3;
;             const int rl = ai * 128 + wr * 64 + m * 16 + fr;
;             const size_t off = (size_t)(prow0 + rl) * DM + col0;
;             f32x4 cur[2][2];
; #pragma unroll
;             for (int bj = 0; bj < 2; ++bj) { cur[bj][0] = *(const f32x4*)(xin + off + bj * 128); cur[bj][1] = *(const f32x4*)(xin + off + bj * 128 + 4); }
;             float ss = 0.f;
; #pragma unroll
;             for (int bj = 0; bj < 2; ++bj) {
;                 f32x4 dl0 = gv[bj][0] * acc[ai][bj][m][0], dl1 = gv[bj][1] * acc[ai][bj][m][1];
;                 bf16* dp = d1 + (size_t)(u.pm * 256 + rl) * DM + col0 + bj * 128;
;                 if (dmode == 2) {
;                     const u32x4 dw = *(const u32x4*)dp;
;                     dl0 += (f32x4){bflo(dw[0]), bfhi(dw[0]), bflo(dw[1]), bfhi(dw[1])}; dl1 += (f32x4){bflo(dw[2]), bfhi(dw[2]), bflo(dw[3]), bfhi(dw[3])};
;                 }
;                 const f32x4 x0 = cur[bj][0] + dl0, x1 = cur[bj][1] + dl1;
;                 if (dmode == 1) { u32x4 dw; dw.x = cvt_pk_bf16(dl0[0], dl0[1]); dw.y = cvt_pk_bf16(dl0[2], dl0[3]); dw.z = cvt_pk_bf16(dl1[0], dl1[1]); dw.w = cvt_pk_bf16(dl1[2], dl1[3]); *(u32x4*)dp = dw; }
;                 else { *(f32x4*)(xout + off + bj * 128) = x0; *(f32x4*)(xout + off + bj * 128 + 4) = x1; }
;                 if (has_next) {
;                     ss += (x0[0] * x0[0] + x0[1] * x0[1]) + (x0[2] * x0[2] + x0[3] * x0[3]) + (x1[0] * x1[0] + x1[1] * x1[1]) + (x1[2] * x1[2] + x1[3] * x1[3]);
;                     const f32x4 y0 = x0 * gm[bj][0], y1 = x1 * gm[bj][1];
;                     u32x4 w; w.x = cvt_pk_bf16(y0[0], y0[1]); w.y = cvt_pk_bf16(y0[2], y0[3]); w.z = cvt_pk_bf16(y1[0], y1[1]); w.w = cvt_pk_bf16(y1[2], y1[3]);
;                     *(u32x4*)(xb + (size_t)(u.pm * 256 + rl) * DM + col0 + bj * 128) = w;
;                 }
;             }
;             if (has_next) {
;                 ss += __shfl_xor(ss, 16); ss += __shfl_xor(ss, 32);
;                 if (fq == 0) atomicAdd(rowss_next + u.pm * 256 + rl, ss);
	v_pk_fma_f32 v[50:51], v[50:51], v[38:39], v[70:71]
	v_cvt_pk_bf16_f32 v62, v62, v63
	v_cvt_pk_bf16_f32 v63, v64, v65
	v_cvt_pk_bf16_f32 v64, v76, v77
	v_cvt_pk_bf16_f32 v65, v66, v67
	global_store_dwordx4 v[94:95], v[62:65], off offset:256
	v_pk_fma_f32 v[48:49], v[48:49], v[36:37], v[68:69]
	s_waitcnt vmcnt(3)
	v_pk_fma_f32 v[62:63], v[46:47], v[42:43], v[74:75]
	v_pk_fma_f32 v[64:65], v[44:45], v[40:41], v[72:73]
	v_pk_mul_f32 v[46:47], v[182:183], v[50:51]
	v_pk_mul_f32 v[44:45], v[184:185], v[48:49]
	v_pk_mul_f32 v[66:67], v[186:187], v[62:63]
	v_pk_mul_f32 v[68:69], v[188:189], v[64:65]
	v_cvt_pk_bf16_f32 v44, v44, v45
	v_cvt_pk_bf16_f32 v45, v46, v47
	v_cvt_pk_bf16_f32 v46, v68, v69
	v_cvt_pk_bf16_f32 v47, v66, v67
	global_store_dwordx4 v[60:61], v[44:47], off offset:256
	s_nop 1
	v_mul_f32_e32 v45, v49, v49
	v_mul_f32_e32 v46, v51, v51
	v_fmac_f32_e32 v45, v48, v48
	v_fmac_f32_e32 v46, v50, v50
	v_add_f32_e32 v45, v45, v46
	v_mul_f32_e32 v46, v65, v65
	v_mul_f32_e32 v44, v63, v63
	v_fmac_f32_e32 v46, v64, v64
	v_fmac_f32_e32 v44, v62, v62
	v_add_f32_e32 v45, v45, v46
	v_add_f32_e32 v44, v44, v45
	v_add_f32_e32 v44, v44, v78
	ds_bpermute_b32 v45, v142, v44
	s_waitcnt lgkmcnt(0)
	v_add_f32_e32 v44, v44, v45
	ds_bpermute_b32 v45, v143, v44
	s_and_saveexec_b64 s[4:5], s[38:39]
	s_cbranch_execz .LBB0_689
	v_lshl_add_u64 v[46:47], s[34:35], 2, v[172:173]
	s_waitcnt lgkmcnt(0)
	v_add_f32_e32 v44, v44, v45
	v_mov_b32_e32 v249, v44
.LBB0_689:
	s_or_b64 exec, exec, s[4:5]
	v_add_u32_e32 v44, s18, v210
	s_waitcnt lgkmcnt(0)
	v_ashrrev_i32_e32 v45, 31, v44
	v_lshlrev_b64 v[44:45], 12, v[44:45]
	v_lshl_add_u64 v[48:49], v[198:199], 0, v[44:45]
	global_load_dwordx4 v[60:63], v[48:49], off
	global_load_dwordx4 v[64:67], v[48:49], off offset:16
	global_load_dwordx4 v[44:47], v[48:49], off offset:512
	s_nop 0
	global_load_dwordx4 v[48:51], v[48:49], off offset:528
	v_add_u32_e32 v68, s34, v210
	v_ashrrev_i32_e32 v69, 31, v68
	v_lshlrev_b64 v[72:73], 11, v[68:69]
	v_pk_mul_f32 v[70:71], v[34:35], v[58:59]
	v_pk_mul_f32 v[68:69], v[32:33], v[56:57]
	v_pk_mul_f32 v[76:77], v[28:29], v[52:53]
	v_pk_mul_f32 v[74:75], v[30:31], v[54:55]
	v_lshl_add_u64 v[78:79], s[78:79], 0, v[72:73]
	v_lshl_add_u64 v[78:79], v[78:79], 0, v[200:201]
	v_cvt_pk_bf16_f32 v68, v68, v69
	v_cvt_pk_bf16_f32 v69, v70, v71
	v_cvt_pk_bf16_f32 v70, v76, v77
	v_cvt_pk_bf16_f32 v71, v74, v75
	global_store_dwordx4 v[78:79], v[68:71], off
	s_waitcnt vmcnt(4)
	v_pk_fma_f32 v[34:35], v[34:35], v[58:59], v[62:63]
	v_pk_fma_f32 v[32:33], v[32:33], v[56:57], v[60:61]
	v_mul_f32_e32 v61, v35, v35
	v_mul_f32_e32 v60, v33, v33
	s_waitcnt vmcnt(3)
	v_pk_fma_f32 v[28:29], v[28:29], v[52:53], v[64:65]
	v_fmac_f32_e32 v60, v32, v32
	v_fmac_f32_e32 v61, v34, v34
	v_add_f32_e32 v60, v60, v61
	v_mul_f32_e32 v61, v29, v29
	v_pk_fma_f32 v[30:31], v[30:31], v[54:55], v[66:67]
	v_fmac_f32_e32 v61, v28, v28
	v_add_f32_e32 v60, v60, v61
	v_mul_f32_e32 v61, v31, v31
	v_fmac_f32_e32 v61, v30, v30
	v_pk_mul_f32 v[32:33], v[192:193], v[32:33]
	v_pk_mul_f32 v[28:29], v[196:197], v[28:29]
	v_add_f32_e32 v62, v61, v60
	v_pk_mul_f32 v[34:35], v[190:191], v[34:35]
	v_pk_mul_f32 v[60:61], v[194:195], v[30:31]
	v_cvt_pk_bf16_f32 v30, v32, v33
	v_cvt_pk_bf16_f32 v32, v28, v29
	v_lshl_add_u64 v[28:29], s[64:65], 0, v[72:73]
	v_cvt_pk_bf16_f32 v31, v34, v35
	v_cvt_pk_bf16_f32 v33, v60, v61
	v_lshl_add_u64 v[28:29], v[28:29], 0, v[200:201]
	global_store_dwordx4 v[28:29], v[30:33], off
	v_pk_mul_f32 v[34:35], v[22:23], v[42:43]
	v_pk_mul_f32 v[60:61], v[20:21], v[40:41]
	v_pk_mul_f32 v[32:33], v[26:27], v[38:39]
	v_pk_mul_f32 v[30:31], v[24:25], v[36:37]
	s_waitcnt vmcnt(3)
	v_pk_fma_f32 v[26:27], v[26:27], v[38:39], v[46:47]
	v_cvt_pk_bf16_f32 v30, v30, v31
	v_cvt_pk_bf16_f32 v31, v32, v33
	v_cvt_pk_bf16_f32 v32, v60, v61
	v_cvt_pk_bf16_f32 v33, v34, v35
	global_store_dwordx4 v[78:79], v[30:33], off offset:256
	v_pk_fma_f32 v[24:25], v[24:25], v[36:37], v[44:45]
	s_waitcnt vmcnt(3)
	v_pk_fma_f32 v[30:31], v[22:23], v[42:43], v[50:51]
	v_pk_fma_f32 v[32:33], v[20:21], v[40:41], v[48:49]
	v_pk_mul_f32 v[22:23], v[182:183], v[26:27]
	v_pk_mul_f32 v[20:21], v[184:185], v[24:25]
	v_pk_mul_f32 v[34:35], v[186:187], v[30:31]
	v_pk_mul_f32 v[44:45], v[188:189], v[32:33]
	v_cvt_pk_bf16_f32 v20, v20, v21
	v_cvt_pk_bf16_f32 v21, v22, v23
	v_cvt_pk_bf16_f32 v22, v44, v45
	v_cvt_pk_bf16_f32 v23, v34, v35
	global_store_dwordx4 v[28:29], v[20:23], off offset:256
	s_nop 1
	v_mul_f32_e32 v21, v25, v25
	v_mul_f32_e32 v22, v27, v27
	v_fmac_f32_e32 v21, v24, v24
	v_fmac_f32_e32 v22, v26, v26
	v_add_f32_e32 v21, v21, v22
	v_mul_f32_e32 v22, v33, v33
	v_mul_f32_e32 v20, v31, v31
	v_fmac_f32_e32 v22, v32, v32
	v_fmac_f32_e32 v20, v30, v30
	v_add_f32_e32 v21, v21, v22
	v_add_f32_e32 v20, v20, v21
	v_add_f32_e32 v20, v20, v62
	ds_bpermute_b32 v21, v142, v20
	s_waitcnt lgkmcnt(0)
	v_add_f32_e32 v20, v20, v21
	ds_bpermute_b32 v21, v143, v20
	s_and_saveexec_b64 s[4:5], s[38:39]
	s_cbranch_execz .LBB0_691
	v_lshl_add_u64 v[22:23], s[34:35], 2, v[174:175]
	s_waitcnt lgkmcnt(0)
	v_add_f32_e32 v20, v20, v21
	v_mov_b32_e32 v250, v20
; __device__ __forceinline__ float bflo(unsigned w) { return __uint_as_float(w << 16); }
;     __device__ __forceinline__ void operator()(const pg8::f32x4 (&acc)[2][2][4][2], const pg8::Unit& u, int wr, int wc, int fr, int fq) const {
;     ...
;         for (int it = 0; it < 8; ++it) {
;             const int ai = it >> 2, m = it & 3;
;             const int rl = ai * 128 + wr * 64 + m * 16 + fr;
;             const size_t off = (size_t)(prow0 + rl) * DM + col0;
;             f32x4 cur[2][2];
; #pragma unroll
;             for (int bj = 0; bj < 2; ++bj) { cur[bj][0] = *(const f32x4*)(xin + off + bj * 128); cur[bj][1] = *(const f32x4*)(xin + off + bj * 128 + 4); }
;             float ss = 0.f;
; #pragma unroll
;             for (int bj = 0; bj < 2; ++bj) {
;                 f32x4 dl0 = gv[bj][0] * acc[ai][bj][m][0], dl1 = gv[bj][1] * acc[ai][bj][m][1];
;                 bf16* dp = d1 + (size_t)(u.pm * 256 + rl) * DM + col0 + bj * 128;
;                 if (dmode == 2) {
;                     const u32x4 dw = *(const u32x4*)dp;
;                     dl0 += (f32x4){bflo(dw[0]), bfhi(dw[0]), bflo(dw[1]), bfhi(dw[1])}; dl1 += (f32x4){bflo(dw[2]), bfhi(dw[2]), bflo(dw[3]), bfhi(dw[3])};
;                 }
;                 const f32x4 x0 = cur[bj][0] + dl0, x1 = cur[bj][1] + dl1;
;                 if (dmode == 1) { u32x4 dw; dw.x = cvt_pk_bf16(dl0[0], dl0[1]); dw.y = cvt_pk_bf16(dl0[2], dl0[3]); dw.z = cvt_pk_bf16(dl1[0], dl1[1]); dw.w = cvt_pk_bf16(dl1[2], dl1[3]); *(u32x4*)dp = dw; }
;                 else { *(f32x4*)(xout + off + bj * 128) = x0; *(f32x4*)(xout + off + bj * 128 + 4) = x1; }
;                 if (has_next) {
;                     ss += (x0[0] * x0[0] + x0[1] * x0[1]) + (x0[2] * x0[2] + x0[3] * x0[3]) + (x1[0] * x1[0] + x1[1] * x1[1]) + (x1[2] * x1[2] + x1[3] * x1[3]);
;                     const f32x4 y0 = x0 * gm[bj][0], y1 = x1 * gm[bj][1];
;                     u32x4 w; w.x = cvt_pk_bf16(y0[0], y0[1]); w.y = cvt_pk_bf16(y0[2], y0[3]); w.z = cvt_pk_bf16(y1[0], y1[1]); w.w = cvt_pk_bf16(y1[2], y1[3]);
;                     *(u32x4*)(xb + (size_t)(u.pm * 256 + rl) * DM + col0 + bj * 128) = w;
;                 }
;             }
;             if (has_next) {
;                 ss += __shfl_xor(ss, 16); ss += __shfl_xor(ss, 32);
;                 if (fq == 0) atomicAdd(rowss_next + u.pm * 256 + rl, ss);
.LBB0_691:
	s_or_b64 exec, exec, s[4:5]
	v_add_u32_e32 v20, s18, v212
	s_waitcnt lgkmcnt(0)
	v_ashrrev_i32_e32 v21, 31, v20
	v_lshlrev_b64 v[20:21], 12, v[20:21]
	v_lshl_add_u64 v[24:25], v[198:199], 0, v[20:21]
	global_load_dwordx4 v[28:31], v[24:25], off
	global_load_dwordx4 v[32:35], v[24:25], off offset:16
	global_load_dwordx4 v[20:23], v[24:25], off offset:512
	s_nop 0
	global_load_dwordx4 v[24:27], v[24:25], off offset:528
	v_add_u32_e32 v44, s34, v212
	v_ashrrev_i32_e32 v45, 31, v44
	v_lshlrev_b64 v[48:49], 11, v[44:45]
	v_pk_mul_f32 v[46:47], v[18:19], v[58:59]
	v_pk_mul_f32 v[44:45], v[16:17], v[56:57]
	v_pk_mul_f32 v[60:61], v[12:13], v[52:53]
	v_pk_mul_f32 v[50:51], v[14:15], v[54:55]
	v_lshl_add_u64 v[62:63], s[78:79], 0, v[48:49]
	v_lshl_add_u64 v[62:63], v[62:63], 0, v[200:201]
	v_cvt_pk_bf16_f32 v44, v44, v45
	v_cvt_pk_bf16_f32 v45, v46, v47
	v_cvt_pk_bf16_f32 v46, v60, v61
	v_cvt_pk_bf16_f32 v47, v50, v51
	global_store_dwordx4 v[62:63], v[44:47], off
	s_waitcnt vmcnt(4)
	v_pk_fma_f32 v[18:19], v[18:19], v[58:59], v[30:31]
	v_pk_fma_f32 v[16:17], v[16:17], v[56:57], v[28:29]
	v_mul_f32_e32 v29, v19, v19
	v_mul_f32_e32 v28, v17, v17
	s_waitcnt vmcnt(3)
	v_pk_fma_f32 v[12:13], v[12:13], v[52:53], v[32:33]
	v_fmac_f32_e32 v28, v16, v16
	v_fmac_f32_e32 v29, v18, v18
	v_add_f32_e32 v28, v28, v29
	v_mul_f32_e32 v29, v13, v13
	v_pk_fma_f32 v[14:15], v[14:15], v[54:55], v[34:35]
	v_fmac_f32_e32 v29, v12, v12
	v_add_f32_e32 v28, v28, v29
	v_mul_f32_e32 v29, v15, v15
	v_fmac_f32_e32 v29, v14, v14
	v_pk_mul_f32 v[16:17], v[192:193], v[16:17]
	v_pk_mul_f32 v[12:13], v[196:197], v[12:13]
	v_add_f32_e32 v30, v29, v28
	v_pk_mul_f32 v[18:19], v[190:191], v[18:19]
	v_pk_mul_f32 v[28:29], v[194:195], v[14:15]
	v_cvt_pk_bf16_f32 v14, v16, v17
	v_cvt_pk_bf16_f32 v16, v12, v13
	v_lshl_add_u64 v[12:13], s[64:65], 0, v[48:49]
	v_cvt_pk_bf16_f32 v15, v18, v19
	v_cvt_pk_bf16_f32 v17, v28, v29
	v_lshl_add_u64 v[12:13], v[12:13], 0, v[200:201]
	global_store_dwordx4 v[12:13], v[14:17], off
	v_pk_mul_f32 v[18:19], v[6:7], v[42:43]
	v_pk_mul_f32 v[28:29], v[4:5], v[40:41]
	v_pk_mul_f32 v[16:17], v[10:11], v[38:39]
	v_pk_mul_f32 v[14:15], v[8:9], v[36:37]
	s_waitcnt vmcnt(3)
	v_pk_fma_f32 v[10:11], v[10:11], v[38:39], v[22:23]
	v_cvt_pk_bf16_f32 v14, v14, v15
	v_cvt_pk_bf16_f32 v15, v16, v17
	v_cvt_pk_bf16_f32 v16, v28, v29
	v_cvt_pk_bf16_f32 v17, v18, v19
	global_store_dwordx4 v[62:63], v[14:17], off offset:256
	v_pk_fma_f32 v[8:9], v[8:9], v[36:37], v[20:21]
	s_waitcnt vmcnt(3)
	v_pk_fma_f32 v[14:15], v[6:7], v[42:43], v[26:27]
	v_pk_fma_f32 v[16:17], v[4:5], v[40:41], v[24:25]
	v_pk_mul_f32 v[6:7], v[182:183], v[10:11]
	v_pk_mul_f32 v[4:5], v[184:185], v[8:9]
	v_pk_mul_f32 v[18:19], v[186:187], v[14:15]
	v_pk_mul_f32 v[20:21], v[188:189], v[16:17]
	v_cvt_pk_bf16_f32 v4, v4, v5
	v_cvt_pk_bf16_f32 v5, v6, v7
	v_cvt_pk_bf16_f32 v6, v20, v21
	v_cvt_pk_bf16_f32 v7, v18, v19
	global_store_dwordx4 v[12:13], v[4:7], off offset:256
	s_nop 1
	v_mul_f32_e32 v5, v9, v9
	v_mul_f32_e32 v6, v11, v11
	v_fmac_f32_e32 v5, v8, v8
	v_fmac_f32_e32 v6, v10, v10
	v_add_f32_e32 v5, v5, v6
	v_mul_f32_e32 v6, v17, v17
	v_mul_f32_e32 v4, v15, v15
	v_fmac_f32_e32 v6, v16, v16
	v_fmac_f32_e32 v4, v14, v14
	v_add_f32_e32 v5, v5, v6
	v_add_f32_e32 v4, v4, v5
	v_add_f32_e32 v4, v4, v30
	ds_bpermute_b32 v5, v142, v4
	s_waitcnt lgkmcnt(0)
	v_add_f32_e32 v4, v4, v5
	ds_bpermute_b32 v5, v143, v4
	s_and_saveexec_b64 s[4:5], s[38:39]
	s_cbranch_execz .LBB0_693
	v_lshl_add_u64 v[6:7], s[34:35], 2, v[176:177]
	s_waitcnt lgkmcnt(0)
	v_add_f32_e32 v4, v4, v5
	v_lshl_add_u64 v[240:241], s[34:35], 2, v[168:169]
	global_atomic_add_f32 v[240:241], v244, off
	global_atomic_add_f32 v[240:241], v245, off offset:64
	global_atomic_add_f32 v[240:241], v246, off offset:128
	global_atomic_add_f32 v[240:241], v247, off offset:192
	v_lshl_add_u64 v[242:243], s[34:35], 2, v[170:171]
	global_atomic_add_f32 v[242:243], v248, off offset:512
	v_lshl_add_u64 v[242:243], s[34:35], 2, v[172:173]
	global_atomic_add_f32 v[242:243], v249, off offset:512
	v_lshl_add_u64 v[242:243], s[34:35], 2, v[174:175]
	global_atomic_add_f32 v[242:243], v250, off offset:512
	global_atomic_add_f32 v[6:7], v4, off offset:512

; __device__ __forceinline__ float bflo(unsigned w) { return __uint_as_float(w << 16); }
; __device__ __forceinline__ float bfhi(unsigned w) { return __uint_as_float(w & 0xffff0000u); }
;     __device__ __forceinline__ void operator()(const pg8::f32x4 (&acc)[2][2][4][2], const pg8::Unit& u, int wr, int wc, int fr, int fq) const {
;     ...
;             for (int bj = 0; bj < 2; ++bj) { cur[bj][0] = *(const f32x4*)(xin + off + bj * 128); cur[bj][1] = *(const f32x4*)(xin + off + bj * 128 + 4); }
;             float ss = 0.f;
; #pragma unroll
;             for (int bj = 0; bj < 2; ++bj) {
;                 f32x4 dl0 = gv[bj][0] * acc[ai][bj][m][0], dl1 = gv[bj][1] * acc[ai][bj][m][1];
;                 bf16* dp = d1 + (size_t)(u.pm * 256 + rl) * DM + col0 + bj * 128;
;                 if (dmode == 2) {
;                     const u32x4 dw = *(const u32x4*)dp;
;                     dl0 += (f32x4){bflo(dw[0]), bfhi(dw[0]), bflo(dw[1]), bfhi(dw[1])}; dl1 += (f32x4){bflo(dw[2]), bfhi(dw[2]), bflo(dw[3]), bfhi(dw[3])};
;                 }
;                 const f32x4 x0 = cur[bj][0] + dl0, x1 = cur[bj][1] + dl1;
;                 if (dmode == 1) { u32x4 dw; dw.x = cvt_pk_bf16(dl0[0], dl0[1]); dw.y = cvt_pk_bf16(dl0[2], dl0[3]); dw.z = cvt_pk_bf16(dl1[0], dl1[1]); dw.w = cvt_pk_bf16(dl1[2], dl1[3]); *(u32x4*)dp = dw; }
;                 else { *(f32x4*)(xout + off + bj * 128) = x0; *(f32x4*)(xout + off + bj * 128 + 4) = x1; }
;                 if (has_next) {
;                     ss += (x0[0] * x0[0] + x0[1] * x0[1]) + (x0[2] * x0[2] + x0[3] * x0[3]) + (x1[0] * x1[0] + x1[1] * x1[1]) + (x1[2] * x1[2] + x1[3] * x1[3]);
;                     const f32x4 y0 = x0 * gm[bj][0], y1 = x1 * gm[bj][1];
;                     u32x4 w; w.x = cvt_pk_bf16(y0[0], y0[1]); w.y = cvt_pk_bf16(y0[2], y0[3]); w.z = cvt_pk_bf16(y1[0], y1[1]); w.w = cvt_pk_bf16(y1[2], y1[3]);
;                     *(u32x4*)(xb + (size_t)(u.pm * 256 + rl) * DM + col0 + bj * 128) = w;
;                 }
;             }
;             if (has_next) {
;                 ss += __shfl_xor(ss, 16); ss += __shfl_xor(ss, 32);
;                 if (fq == 0) atomicAdd(rowss_next + u.pm * 256 + rl, ss);
.LBB0_729:
	s_ashr_i32 s35, s34, 31
	s_and_b64 vcc, exec, s[40:41]
	s_nop 1
	v_mov_b64_e32 v[140:141], v[240:241]
	v_mov_b64_e32 v[142:143], v[242:243]
	v_lshlrev_b32_e32 v144, 16, v140
	v_and_b32_e32 v145, 0xffff0000, v140
	v_lshlrev_b32_e32 v140, 16, v141
	v_and_b32_e32 v141, 0xffff0000, v141
	v_pk_fma_f32 v[138:139], v[138:139], v[30:31], v[140:141]
	v_lshlrev_b32_e32 v140, 16, v142
	v_and_b32_e32 v141, 0xffff0000, v142
	v_lshlrev_b32_e32 v142, 16, v143
	v_and_b32_e32 v143, 0xffff0000, v143
	v_pk_fma_f32 v[136:137], v[136:137], v[28:29], v[144:145]
	v_pk_fma_f32 v[132:133], v[132:133], v[40:41], v[140:141]
	v_pk_fma_f32 v[134:135], v[134:135], v[42:43], v[142:143]
	v_pk_add_f32 v[138:139], v[154:155], v[138:139]
	v_pk_add_f32 v[136:137], v[152:153], v[136:137]
	v_pk_add_f32 v[134:135], v[150:151], v[134:135]
	v_pk_add_f32 v[132:133], v[148:149], v[132:133]
	global_store_dwordx4 v[200:201], v[136:139], off offset:512
	global_store_dwordx4 v[200:201], v[132:135], off offset:528
	s_cbranch_vccnz .LBB0_733
	v_pk_mul_f32 v[140:141], v[188:189], v[138:139]
	v_mul_f32_e32 v144, v137, v137
	v_mul_f32_e32 v139, v139, v139
	v_mul_f32_e32 v143, v133, v133
	v_fmac_f32_e32 v144, v136, v136
	v_fmac_f32_e32 v139, v138, v138
	v_mul_f32_e32 v142, v135, v135
	v_fmac_f32_e32 v143, v132, v132
	v_add_f32_e32 v138, v144, v139
	v_fmac_f32_e32 v142, v134, v134
	v_add_f32_e32 v138, v143, v138
	v_add_f32_e32 v138, v142, v138
	v_and_b32_e32 v139, 64, v222
	v_add_f32_e32 v144, v216, v138
	v_xor_b32_e32 v138, 16, v222
	v_add_u32_e32 v145, 64, v139
	v_cmp_lt_i32_e32 vcc, v138, v145
	v_pk_mul_f32 v[142:143], v[182:183], v[132:133]
	v_xor_b32_e32 v133, 32, v222
	v_cndmask_b32_e32 v138, v222, v138, vcc
	v_lshlrev_b32_e32 v138, 2, v138
	ds_bpermute_b32 v146, v138, v144
	v_cmp_lt_i32_e32 vcc, v133, v145
	v_pk_mul_f32 v[136:137], v[184:185], v[136:137]
	v_pk_mul_f32 v[138:139], v[186:187], v[134:135]
	v_cndmask_b32_e32 v133, v222, v133, vcc
	s_waitcnt lgkmcnt(0)
	v_add_f32_e32 v132, v144, v146
	v_lshlrev_b32_e32 v133, 2, v133
	ds_bpermute_b32 v133, v133, v132
	v_cvt_pk_bf16_f32 v134, v136, v137
	v_cvt_pk_bf16_f32 v135, v140, v141
	v_cvt_pk_bf16_f32 v136, v142, v143
	v_cvt_pk_bf16_f32 v137, v138, v139
	global_store_dwordx4 v[204:205], v[134:137], off offset:256
	s_and_saveexec_b64 s[4:5], s[36:37]
	s_cbranch_execz .LBB0_732
	v_lshl_add_u64 v[134:135], s[34:35], 2, v[168:169]
	s_waitcnt lgkmcnt(0)
	v_add_f32_e32 v132, v132, v133
	v_mov_b32_e32 v244, v132

; __device__ __forceinline__ float bflo(unsigned w) { return __uint_as_float(w << 16); }
; __device__ __forceinline__ float bfhi(unsigned w) { return __uint_as_float(w & 0xffff0000u); }
;     __device__ __forceinline__ void operator()(const pg8::f32x4 (&acc)[2][2][4][2], const pg8::Unit& u, int wr, int wc, int fr, int fq) const {
;     ...
;             for (int bj = 0; bj < 2; ++bj) { cur[bj][0] = *(const f32x4*)(xin + off + bj * 128); cur[bj][1] = *(const f32x4*)(xin + off + bj * 128 + 4); }
;             float ss = 0.f;
; #pragma unroll
;             for (int bj = 0; bj < 2; ++bj) {
;                 f32x4 dl0 = gv[bj][0] * acc[ai][bj][m][0], dl1 = gv[bj][1] * acc[ai][bj][m][1];
;                 bf16* dp = d1 + (size_t)(u.pm * 256 + rl) * DM + col0 + bj * 128;
;                 if (dmode == 2) {
;                     const u32x4 dw = *(const u32x4*)dp;
;                     dl0 += (f32x4){bflo(dw[0]), bfhi(dw[0]), bflo(dw[1]), bfhi(dw[1])}; dl1 += (f32x4){bflo(dw[2]), bfhi(dw[2]), bflo(dw[3]), bfhi(dw[3])};
;                 }
;                 const f32x4 x0 = cur[bj][0] + dl0, x1 = cur[bj][1] + dl1;
;                 if (dmode == 1) { u32x4 dw; dw.x = cvt_pk_bf16(dl0[0], dl0[1]); dw.y = cvt_pk_bf16(dl0[2], dl0[3]); dw.z = cvt_pk_bf16(dl1[0], dl1[1]); dw.w = cvt_pk_bf16(dl1[2], dl1[3]); *(u32x4*)dp = dw; }
;                 else { *(f32x4*)(xout + off + bj * 128) = x0; *(f32x4*)(xout + off + bj * 128 + 4) = x1; }
;                 if (has_next) {
;                     ss += (x0[0] * x0[0] + x0[1] * x0[1]) + (x0[2] * x0[2] + x0[3] * x0[3]) + (x1[0] * x1[0] + x1[1] * x1[1]) + (x1[2] * x1[2] + x1[3] * x1[3]);
;                     const f32x4 y0 = x0 * gm[bj][0], y1 = x1 * gm[bj][1];
;                     u32x4 w; w.x = cvt_pk_bf16(y0[0], y0[1]); w.y = cvt_pk_bf16(y0[2], y0[3]); w.z = cvt_pk_bf16(y1[0], y1[1]); w.w = cvt_pk_bf16(y1[2], y1[3]);
;                     *(u32x4*)(xb + (size_t)(u.pm * 256 + rl) * DM + col0 + bj * 128) = w;
;                 }
;             }
;             if (has_next) {
;                 ss += __shfl_xor(ss, 16); ss += __shfl_xor(ss, 32);
;                 if (fq == 0) atomicAdd(rowss_next + u.pm * 256 + rl, ss);
.LBB0_735:
	s_and_b64 vcc, exec, s[40:41]
	s_nop 1
	v_mov_b64_e32 v[124:125], v[240:241]
	v_mov_b64_e32 v[126:127], v[242:243]
	v_lshlrev_b32_e32 v128, 16, v124
	v_and_b32_e32 v129, 0xffff0000, v124
	v_lshlrev_b32_e32 v124, 16, v125
	v_and_b32_e32 v125, 0xffff0000, v125
	v_pk_fma_f32 v[122:123], v[122:123], v[30:31], v[124:125]
	v_lshlrev_b32_e32 v124, 16, v126
	v_and_b32_e32 v125, 0xffff0000, v126
	v_lshlrev_b32_e32 v126, 16, v127
	v_and_b32_e32 v127, 0xffff0000, v127
	v_pk_fma_f32 v[120:121], v[120:121], v[28:29], v[128:129]
	v_pk_fma_f32 v[116:117], v[116:117], v[40:41], v[124:125]
	v_pk_fma_f32 v[118:119], v[118:119], v[42:43], v[126:127]
	v_pk_add_f32 v[122:123], v[138:139], v[122:123]
	v_pk_add_f32 v[120:121], v[136:137], v[120:121]
	v_pk_add_f32 v[118:119], v[134:135], v[118:119]
	v_pk_add_f32 v[116:117], v[132:133], v[116:117]
	global_store_dwordx4 v[140:141], v[120:123], off offset:512
	global_store_dwordx4 v[140:141], v[116:119], off offset:528
	s_cbranch_vccnz .LBB0_739
	v_pk_mul_f32 v[124:125], v[188:189], v[122:123]
	v_mul_f32_e32 v128, v121, v121
	v_mul_f32_e32 v123, v123, v123
	v_mul_f32_e32 v127, v117, v117
	v_fmac_f32_e32 v128, v120, v120
	v_fmac_f32_e32 v123, v122, v122
	v_mul_f32_e32 v126, v119, v119
	v_fmac_f32_e32 v127, v116, v116
	v_add_f32_e32 v122, v128, v123
	v_fmac_f32_e32 v126, v118, v118
	v_add_f32_e32 v122, v127, v122
	v_add_f32_e32 v122, v126, v122
	v_and_b32_e32 v123, 64, v222
	v_add_f32_e32 v128, v146, v122
	v_xor_b32_e32 v122, 16, v222
	v_add_u32_e32 v129, 64, v123
	v_cmp_lt_i32_e32 vcc, v122, v129
	v_pk_mul_f32 v[126:127], v[182:183], v[116:117]
	v_xor_b32_e32 v117, 32, v222
	v_cndmask_b32_e32 v122, v222, v122, vcc
	v_lshlrev_b32_e32 v122, 2, v122
	ds_bpermute_b32 v130, v122, v128
	v_cmp_lt_i32_e32 vcc, v117, v129
	v_pk_mul_f32 v[120:121], v[184:185], v[120:121]
	v_pk_mul_f32 v[122:123], v[186:187], v[118:119]
	v_cndmask_b32_e32 v117, v222, v117, vcc
	s_waitcnt lgkmcnt(0)
	v_add_f32_e32 v116, v128, v130
	v_lshlrev_b32_e32 v117, 2, v117
	ds_bpermute_b32 v117, v117, v116
	v_cvt_pk_bf16_f32 v118, v120, v121
	v_cvt_pk_bf16_f32 v119, v124, v125
	v_cvt_pk_bf16_f32 v120, v126, v127
	v_cvt_pk_bf16_f32 v121, v122, v123
	global_store_dwordx4 v[142:143], v[118:121], off offset:256
	s_and_saveexec_b64 s[4:5], s[36:37]
	s_cbranch_execz .LBB0_738
	v_lshl_add_u64 v[118:119], s[34:35], 2, v[168:169]
	s_waitcnt lgkmcnt(0)
	v_add_f32_e32 v116, v116, v117
	v_mov_b32_e32 v245, v116

; __device__ __forceinline__ float bflo(unsigned w) { return __uint_as_float(w << 16); }
; __device__ __forceinline__ float bfhi(unsigned w) { return __uint_as_float(w & 0xffff0000u); }
;     __device__ __forceinline__ void operator()(const pg8::f32x4 (&acc)[2][2][4][2], const pg8::Unit& u, int wr, int wc, int fr, int fq) const {
;     ...
;                 f32x4 dl0 = gv[bj][0] * acc[ai][bj][m][0], dl1 = gv[bj][1] * acc[ai][bj][m][1];
;                 bf16* dp = d1 + (size_t)(u.pm * 256 + rl) * DM + col0 + bj * 128;
;                 if (dmode == 2) {
;                     const u32x4 dw = *(const u32x4*)dp;
;                     dl0 += (f32x4){bflo(dw[0]), bfhi(dw[0]), bflo(dw[1]), bfhi(dw[1])}; dl1 += (f32x4){bflo(dw[2]), bfhi(dw[2]), bflo(dw[3]), bfhi(dw[3])};
;                 }
;                 const f32x4 x0 = cur[bj][0] + dl0, x1 = cur[bj][1] + dl1;
;                 if (dmode == 1) { u32x4 dw; dw.x = cvt_pk_bf16(dl0[0], dl0[1]); dw.y = cvt_pk_bf16(dl0[2], dl0[3]); dw.z = cvt_pk_bf16(dl1[0], dl1[1]); dw.w = cvt_pk_bf16(dl1[2], dl1[3]); *(u32x4*)dp = dw; }
;                 else { *(f32x4*)(xout + off + bj * 128) = x0; *(f32x4*)(xout + off + bj * 128 + 4) = x1; }
;                 if (has_next) {
;                     ss += (x0[0] * x0[0] + x0[1] * x0[1]) + (x0[2] * x0[2] + x0[3] * x0[3]) + (x1[0] * x1[0] + x1[1] * x1[1]) + (x1[2] * x1[2] + x1[3] * x1[3]);
;                     const f32x4 y0 = x0 * gm[bj][0], y1 = x1 * gm[bj][1];
;                     u32x4 w; w.x = cvt_pk_bf16(y0[0], y0[1]); w.y = cvt_pk_bf16(y0[2], y0[3]); w.z = cvt_pk_bf16(y1[0], y1[1]); w.w = cvt_pk_bf16(y1[2], y1[3]);
;                     *(u32x4*)(xb + (size_t)(u.pm * 256 + rl) * DM + col0 + bj * 128) = w;
;                 }
;             }
;             if (has_next) {
;                 ss += __shfl_xor(ss, 16); ss += __shfl_xor(ss, 32);
;                 if (fq == 0) atomicAdd(rowss_next + u.pm * 256 + rl, ss);
.LBB0_741:
	s_and_b64 vcc, exec, s[40:41]
	s_nop 1
	v_mov_b64_e32 v[108:109], v[240:241]
	v_mov_b64_e32 v[110:111], v[242:243]
	v_lshlrev_b32_e32 v112, 16, v108
	v_and_b32_e32 v113, 0xffff0000, v108
	v_lshlrev_b32_e32 v108, 16, v109
	v_and_b32_e32 v109, 0xffff0000, v109
	v_pk_fma_f32 v[106:107], v[106:107], v[30:31], v[108:109]
	v_lshlrev_b32_e32 v108, 16, v110
	v_and_b32_e32 v109, 0xffff0000, v110
	v_lshlrev_b32_e32 v110, 16, v111
	v_and_b32_e32 v111, 0xffff0000, v111
	v_pk_fma_f32 v[104:105], v[104:105], v[28:29], v[112:113]
	v_pk_fma_f32 v[100:101], v[100:101], v[40:41], v[108:109]
	v_pk_fma_f32 v[102:103], v[102:103], v[42:43], v[110:111]
	v_pk_add_f32 v[106:107], v[122:123], v[106:107]
	v_pk_add_f32 v[104:105], v[120:121], v[104:105]
	v_pk_add_f32 v[102:103], v[118:119], v[102:103]
	v_pk_add_f32 v[100:101], v[116:117], v[100:101]
	global_store_dwordx4 v[124:125], v[104:107], off offset:512
	global_store_dwordx4 v[124:125], v[100:103], off offset:528
	s_cbranch_vccnz .LBB0_745
	v_pk_mul_f32 v[108:109], v[188:189], v[106:107]
	v_mul_f32_e32 v112, v105, v105
	v_mul_f32_e32 v107, v107, v107
	v_mul_f32_e32 v111, v101, v101
	v_fmac_f32_e32 v112, v104, v104
	v_fmac_f32_e32 v107, v106, v106
	v_mul_f32_e32 v110, v103, v103
	v_fmac_f32_e32 v111, v100, v100
	v_add_f32_e32 v106, v112, v107
	v_fmac_f32_e32 v110, v102, v102
	v_add_f32_e32 v106, v111, v106
	v_add_f32_e32 v106, v110, v106
	v_and_b32_e32 v107, 64, v222
	v_add_f32_e32 v112, v130, v106
	v_xor_b32_e32 v106, 16, v222
	v_add_u32_e32 v113, 64, v107
	v_cmp_lt_i32_e32 vcc, v106, v113
	v_pk_mul_f32 v[110:111], v[182:183], v[100:101]
	v_xor_b32_e32 v101, 32, v222
	v_cndmask_b32_e32 v106, v222, v106, vcc
	v_lshlrev_b32_e32 v106, 2, v106
	ds_bpermute_b32 v114, v106, v112
	v_cmp_lt_i32_e32 vcc, v101, v113
	v_pk_mul_f32 v[104:105], v[184:185], v[104:105]
	v_pk_mul_f32 v[106:107], v[186:187], v[102:103]
	v_cndmask_b32_e32 v101, v222, v101, vcc
	s_waitcnt lgkmcnt(0)
	v_add_f32_e32 v100, v112, v114
	v_lshlrev_b32_e32 v101, 2, v101
	ds_bpermute_b32 v101, v101, v100
	v_cvt_pk_bf16_f32 v102, v104, v105
	v_cvt_pk_bf16_f32 v103, v108, v109
	v_cvt_pk_bf16_f32 v104, v110, v111
	v_cvt_pk_bf16_f32 v105, v106, v107
	global_store_dwordx4 v[126:127], v[102:105], off offset:256
	s_and_saveexec_b64 s[4:5], s[36:37]
	s_cbranch_execz .LBB0_744
	v_lshl_add_u64 v[102:103], s[34:35], 2, v[168:169]
	s_waitcnt lgkmcnt(0)
	v_add_f32_e32 v100, v100, v101
	v_mov_b32_e32 v246, v100

; __device__ __forceinline__ float bflo(unsigned w) { return __uint_as_float(w << 16); }
; __device__ __forceinline__ float bfhi(unsigned w) { return __uint_as_float(w & 0xffff0000u); }
;     __device__ __forceinline__ void operator()(const pg8::f32x4 (&acc)[2][2][4][2], const pg8::Unit& u, int wr, int wc, int fr, int fq) const {
;     ...
;                 f32x4 dl0 = gv[bj][0] * acc[ai][bj][m][0], dl1 = gv[bj][1] * acc[ai][bj][m][1];
;                 bf16* dp = d1 + (size_t)(u.pm * 256 + rl) * DM + col0 + bj * 128;
;                 if (dmode == 2) {
;                     const u32x4 dw = *(const u32x4*)dp;
;                     dl0 += (f32x4){bflo(dw[0]), bfhi(dw[0]), bflo(dw[1]), bfhi(dw[1])}; dl1 += (f32x4){bflo(dw[2]), bfhi(dw[2]), bflo(dw[3]), bfhi(dw[3])};
;                 }
;                 const f32x4 x0 = cur[bj][0] + dl0, x1 = cur[bj][1] + dl1;
;                 if (dmode == 1) { u32x4 dw; dw.x = cvt_pk_bf16(dl0[0], dl0[1]); dw.y = cvt_pk_bf16(dl0[2], dl0[3]); dw.z = cvt_pk_bf16(dl1[0], dl1[1]); dw.w = cvt_pk_bf16(dl1[2], dl1[3]); *(u32x4*)dp = dw; }
;                 else { *(f32x4*)(xout + off + bj * 128) = x0; *(f32x4*)(xout + off + bj * 128 + 4) = x1; }
;                 if (has_next) {
;                     ss += (x0[0] * x0[0] + x0[1] * x0[1]) + (x0[2] * x0[2] + x0[3] * x0[3]) + (x1[0] * x1[0] + x1[1] * x1[1]) + (x1[2] * x1[2] + x1[3] * x1[3]);
;                     const f32x4 y0 = x0 * gm[bj][0], y1 = x1 * gm[bj][1];
;                     u32x4 w; w.x = cvt_pk_bf16(y0[0], y0[1]); w.y = cvt_pk_bf16(y0[2], y0[3]); w.z = cvt_pk_bf16(y1[0], y1[1]); w.w = cvt_pk_bf16(y1[2], y1[3]);
;                     *(u32x4*)(xb + (size_t)(u.pm * 256 + rl) * DM + col0 + bj * 128) = w;
;                 }
;             }
;             if (has_next) {
;                 ss += __shfl_xor(ss, 16); ss += __shfl_xor(ss, 32);
;                 if (fq == 0) atomicAdd(rowss_next + u.pm * 256 + rl, ss);
.LBB0_747:
	s_and_b64 vcc, exec, s[40:41]
	s_nop 1
	v_mov_b64_e32 v[92:93], v[240:241]
	v_mov_b64_e32 v[94:95], v[242:243]
	v_lshlrev_b32_e32 v96, 16, v92
	v_and_b32_e32 v97, 0xffff0000, v92
	v_lshlrev_b32_e32 v92, 16, v93
	v_and_b32_e32 v93, 0xffff0000, v93
	v_pk_fma_f32 v[90:91], v[90:91], v[30:31], v[92:93]
	v_lshlrev_b32_e32 v92, 16, v94
	v_and_b32_e32 v93, 0xffff0000, v94
	v_lshlrev_b32_e32 v94, 16, v95
	v_and_b32_e32 v95, 0xffff0000, v95
	v_pk_fma_f32 v[88:89], v[88:89], v[28:29], v[96:97]
	v_pk_fma_f32 v[84:85], v[84:85], v[40:41], v[92:93]
	v_pk_fma_f32 v[86:87], v[86:87], v[42:43], v[94:95]
	v_pk_add_f32 v[90:91], v[106:107], v[90:91]
	v_pk_add_f32 v[88:89], v[104:105], v[88:89]
	v_pk_add_f32 v[86:87], v[102:103], v[86:87]
	v_pk_add_f32 v[84:85], v[100:101], v[84:85]
	global_store_dwordx4 v[108:109], v[88:91], off offset:512
	global_store_dwordx4 v[108:109], v[84:87], off offset:528
	s_cbranch_vccnz .LBB0_751
	v_pk_mul_f32 v[92:93], v[188:189], v[90:91]
	v_mul_f32_e32 v96, v89, v89
	v_mul_f32_e32 v91, v91, v91
	v_mul_f32_e32 v95, v85, v85
	v_fmac_f32_e32 v96, v88, v88
	v_fmac_f32_e32 v91, v90, v90
	v_mul_f32_e32 v94, v87, v87
	v_fmac_f32_e32 v95, v84, v84
	v_add_f32_e32 v90, v96, v91
	v_fmac_f32_e32 v94, v86, v86
	v_add_f32_e32 v90, v95, v90
	v_add_f32_e32 v90, v94, v90
	v_and_b32_e32 v91, 64, v222
	v_add_f32_e32 v96, v114, v90
	v_xor_b32_e32 v90, 16, v222
	v_add_u32_e32 v97, 64, v91
	v_cmp_lt_i32_e32 vcc, v90, v97
	v_pk_mul_f32 v[94:95], v[182:183], v[84:85]
	v_xor_b32_e32 v85, 32, v222
	v_cndmask_b32_e32 v90, v222, v90, vcc
	v_lshlrev_b32_e32 v90, 2, v90
	ds_bpermute_b32 v98, v90, v96
	v_cmp_lt_i32_e32 vcc, v85, v97
	v_pk_mul_f32 v[88:89], v[184:185], v[88:89]
	v_pk_mul_f32 v[90:91], v[186:187], v[86:87]
	v_cndmask_b32_e32 v85, v222, v85, vcc
	s_waitcnt lgkmcnt(0)
	v_add_f32_e32 v84, v96, v98
	v_lshlrev_b32_e32 v85, 2, v85
	ds_bpermute_b32 v85, v85, v84
	v_cvt_pk_bf16_f32 v86, v88, v89
	v_cvt_pk_bf16_f32 v87, v92, v93
	v_cvt_pk_bf16_f32 v88, v94, v95
	v_cvt_pk_bf16_f32 v89, v90, v91
	global_store_dwordx4 v[110:111], v[86:89], off offset:256
	s_and_saveexec_b64 s[4:5], s[36:37]
	s_cbranch_execz .LBB0_750
	v_lshl_add_u64 v[86:87], s[34:35], 2, v[168:169]
	s_waitcnt lgkmcnt(0)
	v_add_f32_e32 v84, v84, v85
	v_mov_b32_e32 v247, v84

; __device__ __forceinline__ float bflo(unsigned w) { return __uint_as_float(w << 16); }
; __device__ __forceinline__ float bfhi(unsigned w) { return __uint_as_float(w & 0xffff0000u); }
;     __device__ __forceinline__ void operator()(const pg8::f32x4 (&acc)[2][2][4][2], const pg8::Unit& u, int wr, int wc, int fr, int fq) const {
;     ...
;                 f32x4 dl0 = gv[bj][0] * acc[ai][bj][m][0], dl1 = gv[bj][1] * acc[ai][bj][m][1];
;                 bf16* dp = d1 + (size_t)(u.pm * 256 + rl) * DM + col0 + bj * 128;
;                 if (dmode == 2) {
;                     const u32x4 dw = *(const u32x4*)dp;
;                     dl0 += (f32x4){bflo(dw[0]), bfhi(dw[0]), bflo(dw[1]), bfhi(dw[1])}; dl1 += (f32x4){bflo(dw[2]), bfhi(dw[2]), bflo(dw[3]), bfhi(dw[3])};
;                 }
;                 const f32x4 x0 = cur[bj][0] + dl0, x1 = cur[bj][1] + dl1;
;                 if (dmode == 1) { u32x4 dw; dw.x = cvt_pk_bf16(dl0[0], dl0[1]); dw.y = cvt_pk_bf16(dl0[2], dl0[3]); dw.z = cvt_pk_bf16(dl1[0], dl1[1]); dw.w = cvt_pk_bf16(dl1[2], dl1[3]); *(u32x4*)dp = dw; }
;                 else { *(f32x4*)(xout + off + bj * 128) = x0; *(f32x4*)(xout + off + bj * 128 + 4) = x1; }
;                 if (has_next) {
;                     ss += (x0[0] * x0[0] + x0[1] * x0[1]) + (x0[2] * x0[2] + x0[3] * x0[3]) + (x1[0] * x1[0] + x1[1] * x1[1]) + (x1[2] * x1[2] + x1[3] * x1[3]);
;                     const f32x4 y0 = x0 * gm[bj][0], y1 = x1 * gm[bj][1];
;                     u32x4 w; w.x = cvt_pk_bf16(y0[0], y0[1]); w.y = cvt_pk_bf16(y0[2], y0[3]); w.z = cvt_pk_bf16(y1[0], y1[1]); w.w = cvt_pk_bf16(y1[2], y1[3]);
;                     *(u32x4*)(xb + (size_t)(u.pm * 256 + rl) * DM + col0 + bj * 128) = w;
;                 }
;             }
;             if (has_next) {
;                 ss += __shfl_xor(ss, 16); ss += __shfl_xor(ss, 32);
;                 if (fq == 0) atomicAdd(rowss_next + u.pm * 256 + rl, ss);
.LBB0_753:
	s_and_b64 vcc, exec, s[40:41]
	s_nop 1
	v_mov_b64_e32 v[76:77], v[240:241]
	v_mov_b64_e32 v[78:79], v[242:243]
	v_lshlrev_b32_e32 v80, 16, v76
	v_and_b32_e32 v81, 0xffff0000, v76
	v_lshlrev_b32_e32 v76, 16, v77
	v_and_b32_e32 v77, 0xffff0000, v77
	v_pk_fma_f32 v[74:75], v[74:75], v[30:31], v[76:77]
	v_lshlrev_b32_e32 v76, 16, v78
	v_and_b32_e32 v77, 0xffff0000, v78
	v_lshlrev_b32_e32 v78, 16, v79
	v_and_b32_e32 v79, 0xffff0000, v79
	v_pk_fma_f32 v[72:73], v[72:73], v[28:29], v[80:81]
	v_pk_fma_f32 v[68:69], v[68:69], v[40:41], v[76:77]
	v_pk_fma_f32 v[70:71], v[70:71], v[42:43], v[78:79]
	v_pk_add_f32 v[74:75], v[90:91], v[74:75]
	v_pk_add_f32 v[72:73], v[88:89], v[72:73]
	v_pk_add_f32 v[70:71], v[86:87], v[70:71]
	v_pk_add_f32 v[68:69], v[84:85], v[68:69]
	global_store_dwordx4 v[92:93], v[72:75], off offset:512
	global_store_dwordx4 v[92:93], v[68:71], off offset:528
	s_cbranch_vccnz .LBB0_757
	v_pk_mul_f32 v[76:77], v[188:189], v[74:75]
	v_mul_f32_e32 v80, v73, v73
	v_mul_f32_e32 v75, v75, v75
	v_mul_f32_e32 v79, v69, v69
	v_fmac_f32_e32 v80, v72, v72
	v_fmac_f32_e32 v75, v74, v74
	v_mul_f32_e32 v78, v71, v71
	v_fmac_f32_e32 v79, v68, v68
	v_add_f32_e32 v74, v80, v75
	v_fmac_f32_e32 v78, v70, v70
	v_add_f32_e32 v74, v79, v74
	v_add_f32_e32 v74, v78, v74
	v_and_b32_e32 v75, 64, v222
	v_add_f32_e32 v80, v98, v74
	v_xor_b32_e32 v74, 16, v222
	v_add_u32_e32 v81, 64, v75
	v_cmp_lt_i32_e32 vcc, v74, v81
	v_pk_mul_f32 v[78:79], v[182:183], v[68:69]
	v_xor_b32_e32 v69, 32, v222
	v_cndmask_b32_e32 v74, v222, v74, vcc
	v_lshlrev_b32_e32 v74, 2, v74
	ds_bpermute_b32 v82, v74, v80
	v_cmp_lt_i32_e32 vcc, v69, v81
	v_pk_mul_f32 v[72:73], v[184:185], v[72:73]
	v_pk_mul_f32 v[74:75], v[186:187], v[70:71]
	v_cndmask_b32_e32 v69, v222, v69, vcc
	s_waitcnt lgkmcnt(0)
	v_add_f32_e32 v68, v80, v82
	v_lshlrev_b32_e32 v69, 2, v69
	ds_bpermute_b32 v69, v69, v68
	v_cvt_pk_bf16_f32 v70, v72, v73
	v_cvt_pk_bf16_f32 v71, v76, v77
	v_cvt_pk_bf16_f32 v72, v78, v79
	v_cvt_pk_bf16_f32 v73, v74, v75
	global_store_dwordx4 v[94:95], v[70:73], off offset:256
	s_and_saveexec_b64 s[4:5], s[36:37]
	s_cbranch_execz .LBB0_756
	v_lshl_add_u64 v[70:71], s[34:35], 2, v[170:171]
	s_waitcnt lgkmcnt(0)
	v_add_f32_e32 v68, v68, v69
	v_mov_b32_e32 v248, v68

; __device__ __forceinline__ float bflo(unsigned w) { return __uint_as_float(w << 16); }
; __device__ __forceinline__ float bfhi(unsigned w) { return __uint_as_float(w & 0xffff0000u); }
;     __device__ __forceinline__ void operator()(const pg8::f32x4 (&acc)[2][2][4][2], const pg8::Unit& u, int wr, int wc, int fr, int fq) const {
;     ...
;                 f32x4 dl0 = gv[bj][0] * acc[ai][bj][m][0], dl1 = gv[bj][1] * acc[ai][bj][m][1];
;                 bf16* dp = d1 + (size_t)(u.pm * 256 + rl) * DM + col0 + bj * 128;
;                 if (dmode == 2) {
;                     const u32x4 dw = *(const u32x4*)dp;
;                     dl0 += (f32x4){bflo(dw[0]), bfhi(dw[0]), bflo(dw[1]), bfhi(dw[1])}; dl1 += (f32x4){bflo(dw[2]), bfhi(dw[2]), bflo(dw[3]), bfhi(dw[3])};
;                 }
;                 const f32x4 x0 = cur[bj][0] + dl0, x1 = cur[bj][1] + dl1;
;                 if (dmode == 1) { u32x4 dw; dw.x = cvt_pk_bf16(dl0[0], dl0[1]); dw.y = cvt_pk_bf16(dl0[2], dl0[3]); dw.z = cvt_pk_bf16(dl1[0], dl1[1]); dw.w = cvt_pk_bf16(dl1[2], dl1[3]); *(u32x4*)dp = dw; }
;                 else { *(f32x4*)(xout + off + bj * 128) = x0; *(f32x4*)(xout + off + bj * 128 + 4) = x1; }
;                 if (has_next) {
;                     ss += (x0[0] * x0[0] + x0[1] * x0[1]) + (x0[2] * x0[2] + x0[3] * x0[3]) + (x1[0] * x1[0] + x1[1] * x1[1]) + (x1[2] * x1[2] + x1[3] * x1[3]);
;                     const f32x4 y0 = x0 * gm[bj][0], y1 = x1 * gm[bj][1];
;                     u32x4 w; w.x = cvt_pk_bf16(y0[0], y0[1]); w.y = cvt_pk_bf16(y0[2], y0[3]); w.z = cvt_pk_bf16(y1[0], y1[1]); w.w = cvt_pk_bf16(y1[2], y1[3]);
;                     *(u32x4*)(xb + (size_t)(u.pm * 256 + rl) * DM + col0 + bj * 128) = w;
;                 }
;             }
;             if (has_next) {
;                 ss += __shfl_xor(ss, 16); ss += __shfl_xor(ss, 32);
;                 if (fq == 0) atomicAdd(rowss_next + u.pm * 256 + rl, ss);
.LBB0_759:
	s_and_b64 vcc, exec, s[40:41]
	s_nop 1
	v_mov_b64_e32 v[60:61], v[240:241]
	v_mov_b64_e32 v[62:63], v[242:243]
	v_lshlrev_b32_e32 v64, 16, v60
	v_and_b32_e32 v65, 0xffff0000, v60
	v_lshlrev_b32_e32 v60, 16, v61
	v_and_b32_e32 v61, 0xffff0000, v61
	v_pk_fma_f32 v[58:59], v[58:59], v[30:31], v[60:61]
	v_lshlrev_b32_e32 v60, 16, v62
	v_and_b32_e32 v61, 0xffff0000, v62
	v_lshlrev_b32_e32 v62, 16, v63
	v_and_b32_e32 v63, 0xffff0000, v63
	v_pk_fma_f32 v[56:57], v[56:57], v[28:29], v[64:65]
	v_pk_fma_f32 v[52:53], v[52:53], v[40:41], v[60:61]
	v_pk_fma_f32 v[54:55], v[54:55], v[42:43], v[62:63]
	v_pk_add_f32 v[58:59], v[74:75], v[58:59]
	v_pk_add_f32 v[56:57], v[72:73], v[56:57]
	v_pk_add_f32 v[54:55], v[70:71], v[54:55]
	v_pk_add_f32 v[52:53], v[68:69], v[52:53]
	global_store_dwordx4 v[76:77], v[56:59], off offset:512
	global_store_dwordx4 v[76:77], v[52:55], off offset:528
	s_cbranch_vccnz .LBB0_763
	v_pk_mul_f32 v[60:61], v[188:189], v[58:59]
	v_mul_f32_e32 v64, v57, v57
	v_mul_f32_e32 v59, v59, v59
	v_mul_f32_e32 v63, v53, v53
	v_fmac_f32_e32 v64, v56, v56
	v_fmac_f32_e32 v59, v58, v58
	v_mul_f32_e32 v62, v55, v55
	v_fmac_f32_e32 v63, v52, v52
	v_add_f32_e32 v58, v64, v59
	v_fmac_f32_e32 v62, v54, v54
	v_add_f32_e32 v58, v63, v58
	v_add_f32_e32 v58, v62, v58
	v_and_b32_e32 v59, 64, v222
	v_add_f32_e32 v64, v82, v58
	v_xor_b32_e32 v58, 16, v222
	v_add_u32_e32 v65, 64, v59
	v_cmp_lt_i32_e32 vcc, v58, v65
	v_pk_mul_f32 v[62:63], v[182:183], v[52:53]
	v_xor_b32_e32 v53, 32, v222
	v_cndmask_b32_e32 v58, v222, v58, vcc
	v_lshlrev_b32_e32 v58, 2, v58
	ds_bpermute_b32 v66, v58, v64
	v_cmp_lt_i32_e32 vcc, v53, v65
	v_pk_mul_f32 v[56:57], v[184:185], v[56:57]
	v_pk_mul_f32 v[58:59], v[186:187], v[54:55]
	v_cndmask_b32_e32 v53, v222, v53, vcc
	s_waitcnt lgkmcnt(0)
	v_add_f32_e32 v52, v64, v66
	v_lshlrev_b32_e32 v53, 2, v53
	ds_bpermute_b32 v53, v53, v52
	v_cvt_pk_bf16_f32 v54, v56, v57
	v_cvt_pk_bf16_f32 v55, v60, v61
	v_cvt_pk_bf16_f32 v56, v62, v63
	v_cvt_pk_bf16_f32 v57, v58, v59
	global_store_dwordx4 v[78:79], v[54:57], off offset:256
	s_and_saveexec_b64 s[4:5], s[36:37]
	s_cbranch_execz .LBB0_762
	v_lshl_add_u64 v[54:55], s[34:35], 2, v[172:173]
	s_waitcnt lgkmcnt(0)
	v_add_f32_e32 v52, v52, v53
	v_mov_b32_e32 v249, v52

; __device__ __forceinline__ float bflo(unsigned w) { return __uint_as_float(w << 16); }
; __device__ __forceinline__ float bfhi(unsigned w) { return __uint_as_float(w & 0xffff0000u); }
;     __device__ __forceinline__ void operator()(const pg8::f32x4 (&acc)[2][2][4][2], const pg8::Unit& u, int wr, int wc, int fr, int fq) const {
;     ...
;                 f32x4 dl0 = gv[bj][0] * acc[ai][bj][m][0], dl1 = gv[bj][1] * acc[ai][bj][m][1];
;                 bf16* dp = d1 + (size_t)(u.pm * 256 + rl) * DM + col0 + bj * 128;
;                 if (dmode == 2) {
;                     const u32x4 dw = *(const u32x4*)dp;
;                     dl0 += (f32x4){bflo(dw[0]), bfhi(dw[0]), bflo(dw[1]), bfhi(dw[1])}; dl1 += (f32x4){bflo(dw[2]), bfhi(dw[2]), bflo(dw[3]), bfhi(dw[3])};
;                 }
;                 const f32x4 x0 = cur[bj][0] + dl0, x1 = cur[bj][1] + dl1;
;                 if (dmode == 1) { u32x4 dw; dw.x = cvt_pk_bf16(dl0[0], dl0[1]); dw.y = cvt_pk_bf16(dl0[2], dl0[3]); dw.z = cvt_pk_bf16(dl1[0], dl1[1]); dw.w = cvt_pk_bf16(dl1[2], dl1[3]); *(u32x4*)dp = dw; }
;                 else { *(f32x4*)(xout + off + bj * 128) = x0; *(f32x4*)(xout + off + bj * 128 + 4) = x1; }
;                 if (has_next) {
;                     ss += (x0[0] * x0[0] + x0[1] * x0[1]) + (x0[2] * x0[2] + x0[3] * x0[3]) + (x1[0] * x1[0] + x1[1] * x1[1]) + (x1[2] * x1[2] + x1[3] * x1[3]);
;                     const f32x4 y0 = x0 * gm[bj][0], y1 = x1 * gm[bj][1];
;                     u32x4 w; w.x = cvt_pk_bf16(y0[0], y0[1]); w.y = cvt_pk_bf16(y0[2], y0[3]); w.z = cvt_pk_bf16(y1[0], y1[1]); w.w = cvt_pk_bf16(y1[2], y1[3]);
;                     *(u32x4*)(xb + (size_t)(u.pm * 256 + rl) * DM + col0 + bj * 128) = w;
;                 }
;             }
;             if (has_next) {
;                 ss += __shfl_xor(ss, 16); ss += __shfl_xor(ss, 32);
;                 if (fq == 0) atomicAdd(rowss_next + u.pm * 256 + rl, ss);
.LBB0_765:
	s_and_b64 vcc, exec, s[40:41]
	s_nop 1
	v_mov_b64_e32 v[32:33], v[240:241]
	v_mov_b64_e32 v[34:35], v[242:243]
	v_lshlrev_b32_e32 v36, 16, v32
	v_and_b32_e32 v37, 0xffff0000, v32
	v_lshlrev_b32_e32 v32, 16, v33
	v_and_b32_e32 v33, 0xffff0000, v33
	v_pk_fma_f32 v[26:27], v[26:27], v[30:31], v[32:33]
	v_lshlrev_b32_e32 v32, 16, v34
	v_and_b32_e32 v33, 0xffff0000, v34
	v_lshlrev_b32_e32 v34, 16, v35
	v_and_b32_e32 v35, 0xffff0000, v35
	v_pk_fma_f32 v[24:25], v[24:25], v[28:29], v[36:37]
	v_pk_fma_f32 v[20:21], v[20:21], v[40:41], v[32:33]
	v_pk_fma_f32 v[22:23], v[22:23], v[42:43], v[34:35]
	v_pk_add_f32 v[26:27], v[58:59], v[26:27]
	v_pk_add_f32 v[24:25], v[56:57], v[24:25]
	v_pk_add_f32 v[22:23], v[54:55], v[22:23]
	v_pk_add_f32 v[20:21], v[52:53], v[20:21]
	global_store_dwordx4 v[60:61], v[24:27], off offset:512
	global_store_dwordx4 v[60:61], v[20:23], off offset:528
	s_cbranch_vccnz .LBB0_769
	v_pk_mul_f32 v[32:33], v[188:189], v[26:27]
	v_mul_f32_e32 v36, v25, v25
	v_mul_f32_e32 v27, v27, v27
	v_mul_f32_e32 v35, v21, v21
	v_fmac_f32_e32 v36, v24, v24
	v_fmac_f32_e32 v27, v26, v26
	v_mul_f32_e32 v34, v23, v23
	v_fmac_f32_e32 v35, v20, v20
	v_add_f32_e32 v26, v36, v27
	v_fmac_f32_e32 v34, v22, v22
	v_add_f32_e32 v26, v35, v26
	v_add_f32_e32 v26, v34, v26
	v_and_b32_e32 v27, 64, v222
	v_add_f32_e32 v36, v66, v26
	v_xor_b32_e32 v26, 16, v222
	v_add_u32_e32 v37, 64, v27
	v_cmp_lt_i32_e32 vcc, v26, v37
	v_pk_mul_f32 v[34:35], v[182:183], v[20:21]
	v_xor_b32_e32 v21, 32, v222
	v_cndmask_b32_e32 v26, v222, v26, vcc
	v_lshlrev_b32_e32 v26, 2, v26
	ds_bpermute_b32 v38, v26, v36
	v_cmp_lt_i32_e32 vcc, v21, v37
	v_pk_mul_f32 v[24:25], v[184:185], v[24:25]
	v_pk_mul_f32 v[26:27], v[186:187], v[22:23]
	v_cndmask_b32_e32 v21, v222, v21, vcc
	s_waitcnt lgkmcnt(0)
	v_add_f32_e32 v20, v36, v38
	v_lshlrev_b32_e32 v21, 2, v21
	ds_bpermute_b32 v21, v21, v20
	v_cvt_pk_bf16_f32 v22, v24, v25
	v_cvt_pk_bf16_f32 v23, v32, v33
	v_cvt_pk_bf16_f32 v24, v34, v35
	v_cvt_pk_bf16_f32 v25, v26, v27
	global_store_dwordx4 v[62:63], v[22:25], off offset:256
	s_and_saveexec_b64 s[4:5], s[36:37]
	s_cbranch_execz .LBB0_768
	v_lshl_add_u64 v[22:23], s[34:35], 2, v[174:175]
	s_waitcnt lgkmcnt(0)
	v_add_f32_e32 v20, v20, v21
	v_mov_b32_e32 v250, v20

; __device__ __forceinline__ float bflo(unsigned w) { return __uint_as_float(w << 16); }
; __device__ __forceinline__ float bfhi(unsigned w) { return __uint_as_float(w & 0xffff0000u); }
;     __device__ __forceinline__ void operator()(const pg8::f32x4 (&acc)[2][2][4][2], const pg8::Unit& u, int wr, int wc, int fr, int fq) const {
;     ...
;                 f32x4 dl0 = gv[bj][0] * acc[ai][bj][m][0], dl1 = gv[bj][1] * acc[ai][bj][m][1];
;                 bf16* dp = d1 + (size_t)(u.pm * 256 + rl) * DM + col0 + bj * 128;
;                 if (dmode == 2) {
;                     const u32x4 dw = *(const u32x4*)dp;
;                     dl0 += (f32x4){bflo(dw[0]), bfhi(dw[0]), bflo(dw[1]), bfhi(dw[1])}; dl1 += (f32x4){bflo(dw[2]), bfhi(dw[2]), bflo(dw[3]), bfhi(dw[3])};
;                 }
;                 const f32x4 x0 = cur[bj][0] + dl0, x1 = cur[bj][1] + dl1;
;                 if (dmode == 1) { u32x4 dw; dw.x = cvt_pk_bf16(dl0[0], dl0[1]); dw.y = cvt_pk_bf16(dl0[2], dl0[3]); dw.z = cvt_pk_bf16(dl1[0], dl1[1]); dw.w = cvt_pk_bf16(dl1[2], dl1[3]); *(u32x4*)dp = dw; }
;                 else { *(f32x4*)(xout + off + bj * 128) = x0; *(f32x4*)(xout + off + bj * 128 + 4) = x1; }
;                 if (has_next) {
;                     ss += (x0[0] * x0[0] + x0[1] * x0[1]) + (x0[2] * x0[2] + x0[3] * x0[3]) + (x1[0] * x1[0] + x1[1] * x1[1]) + (x1[2] * x1[2] + x1[3] * x1[3]);
;                     const f32x4 y0 = x0 * gm[bj][0], y1 = x1 * gm[bj][1];
;                     u32x4 w; w.x = cvt_pk_bf16(y0[0], y0[1]); w.y = cvt_pk_bf16(y0[2], y0[3]); w.z = cvt_pk_bf16(y1[0], y1[1]); w.w = cvt_pk_bf16(y1[2], y1[3]);
;                     *(u32x4*)(xb + (size_t)(u.pm * 256 + rl) * DM + col0 + bj * 128) = w;
;                 }
;             }
;             if (has_next) {
;                 ss += __shfl_xor(ss, 16); ss += __shfl_xor(ss, 32);
;                 if (fq == 0) atomicAdd(rowss_next + u.pm * 256 + rl, ss);
.LBB0_771:
	v_readlane_b32 s74, v254, 33
	s_and_b64 vcc, exec, s[40:41]
	v_readlane_b32 s75, v254, 34
	s_nop 1
	v_mov_b64_e32 v[12:13], v[240:241]
	v_mov_b64_e32 v[14:15], v[242:243]
	v_lshlrev_b32_e32 v16, 16, v12
	v_and_b32_e32 v17, 0xffff0000, v12
	v_lshlrev_b32_e32 v12, 16, v13
	v_and_b32_e32 v13, 0xffff0000, v13
	v_pk_fma_f32 v[10:11], v[10:11], v[30:31], v[12:13]
	v_lshlrev_b32_e32 v12, 16, v14
	v_and_b32_e32 v13, 0xffff0000, v14
	v_lshlrev_b32_e32 v14, 16, v15
	v_and_b32_e32 v15, 0xffff0000, v15
	v_pk_fma_f32 v[8:9], v[8:9], v[28:29], v[16:17]
	v_pk_fma_f32 v[4:5], v[4:5], v[40:41], v[12:13]
	v_pk_fma_f32 v[6:7], v[6:7], v[42:43], v[14:15]
	v_pk_add_f32 v[10:11], v[26:27], v[10:11]
	v_pk_add_f32 v[8:9], v[24:25], v[8:9]
	v_pk_add_f32 v[6:7], v[22:23], v[6:7]
	v_pk_add_f32 v[4:5], v[20:21], v[4:5]
	global_store_dwordx4 v[32:33], v[8:11], off offset:512
	global_store_dwordx4 v[32:33], v[4:7], off offset:528
	s_cbranch_vccnz .LBB0_775
	v_pk_mul_f32 v[12:13], v[188:189], v[10:11]
	v_mul_f32_e32 v16, v9, v9
	v_mul_f32_e32 v11, v11, v11
	v_mul_f32_e32 v15, v5, v5
	v_fmac_f32_e32 v16, v8, v8
	v_fmac_f32_e32 v11, v10, v10
	v_mul_f32_e32 v14, v7, v7
	v_fmac_f32_e32 v15, v4, v4
	v_add_f32_e32 v10, v16, v11
	v_fmac_f32_e32 v14, v6, v6
	v_add_f32_e32 v10, v15, v10
	v_add_f32_e32 v10, v14, v10
	v_and_b32_e32 v11, 64, v222
	v_add_f32_e32 v16, v38, v10
	v_xor_b32_e32 v10, 16, v222
	v_add_u32_e32 v17, 64, v11
	v_cmp_lt_i32_e32 vcc, v10, v17
	v_pk_mul_f32 v[14:15], v[182:183], v[4:5]
	v_xor_b32_e32 v5, 32, v222
	v_cndmask_b32_e32 v10, v222, v10, vcc
	v_lshlrev_b32_e32 v10, 2, v10
	ds_bpermute_b32 v18, v10, v16
	v_cmp_lt_i32_e32 vcc, v5, v17
	v_pk_mul_f32 v[8:9], v[184:185], v[8:9]
	v_pk_mul_f32 v[10:11], v[186:187], v[6:7]
	v_cndmask_b32_e32 v5, v222, v5, vcc
	s_waitcnt lgkmcnt(0)
	v_add_f32_e32 v4, v16, v18
	v_lshlrev_b32_e32 v5, 2, v5
	ds_bpermute_b32 v5, v5, v4
	v_cvt_pk_bf16_f32 v6, v8, v9
	v_cvt_pk_bf16_f32 v7, v12, v13
	v_cvt_pk_bf16_f32 v8, v14, v15
	v_cvt_pk_bf16_f32 v9, v10, v11
	global_store_dwordx4 v[34:35], v[6:9], off offset:256
	s_and_saveexec_b64 s[4:5], s[36:37]
	s_cbranch_execz .LBB0_774
	v_lshl_add_u64 v[6:7], s[34:35], 2, v[176:177]
	s_waitcnt lgkmcnt(0)
	v_add_f32_e32 v4, v4, v5
	v_lshl_add_u64 v[240:241], s[34:35], 2, v[168:169]
	global_atomic_add_f32 v[240:241], v244, off
	global_atomic_add_f32 v[240:241], v245, off offset:64
	global_atomic_add_f32 v[240:241], v246, off offset:128
	global_atomic_add_f32 v[240:241], v247, off offset:192
	v_lshl_add_u64 v[242:243], s[34:35], 2, v[170:171]
	global_atomic_add_f32 v[242:243], v248, off offset:512
	v_lshl_add_u64 v[242:243], s[34:35], 2, v[172:173]
	global_atomic_add_f32 v[242:243], v249, off offset:512
	v_lshl_add_u64 v[242:243], s[34:35], 2, v[174:175]
	global_atomic_add_f32 v[242:243], v250, off offset:512
	global_atomic_add_f32 v[6:7], v4, off offset:512
